# g24 + P6/P9 out/down-projection GEMM tiles also distributed dynamically per XCD
# speedup vs baseline: 1.0231x; 1.0012x over previous
; template <class F> DI void for_tiles_st(int ntm, int ntn, const Sched& sc, F f) {
;   if ((ntn & 7) == 0) {
;     const int nsn = ntn >> 3, nsuper = (ntm >> 3) * nsn;
;     for (int sp = sc.xd; sp < nsuper; sp += sc.nx) {
;       const int sm = sp / nsn, sn = sp - sm * nsn;
;       for (int qq = sc.rank; qq < 64; qq += sc.nloc) f(sm * 8 + (qq >> 3), sn * 8 + (qq & 7));
; DI void phase6(const Params& p, const Sched& sched, unsigned char* smem) {
;   XBlk xl{(const u16*)(p.ws + OFF_KVU), Tn};
;   const float* mod = (const float*)(p.ws + OFF_MOD);
;   u16* x1b = (u16*)(p.ws + OFF_MA);
;   for_tiles_st(256, 8, sched, [&](int tm, int tn) {
;     gemm_tile<8>((const u16*)(p.ws + OFF_WO), 1024, tn * 128, tm * 256, 1024, xl, [&](f32x4 (&acc)[4][8], int fb, int tb, int lr, int lq, int wf, int wt) {
.LBB0_806:
	s_or_b64 exec, exec, s[0:1]
	s_add_u32 s12, s42, 0x23b00800
	s_addc_u32 s13, s43, 0
	s_cmp_lt_i32 s74, 32
	s_cselect_b64 s[14:15], -1, 0
	s_cmp_gt_i32 s74, 31
	s_waitcnt lgkmcnt(0)
	s_barrier
	s_cbranch_scc1 .LBB0_814
	s_add_u32 s4, s42, 0xa00000
	s_addc_u32 s5, s43, 0
	s_add_u32 s6, s42, 0x33f00800
	s_addc_u32 s7, s43, 0
	s_cmp_lt_i32 s75, 64
	s_cselect_b64 s[0:1], -1, 0
	v_cndmask_b32_e64 v0, 0, 1, s[0:1]
	s_add_u32 s8, s42, 0xa10000
	s_addc_u32 s9, s43, 0
	s_lshl_b32 s20, s74, 3
	s_lshl_b32 s21, s79, 3
	v_cmp_ne_u32_e64 s[0:1], 1, v0
	s_movk_i32 s22, 0xc0
	s_movk_i32 s23, 0x80
	v_mov_b32_e32 v153, 0
	s_mov_b32 s24, 0xa20000
	s_mov_b32 s25, 0x34300000
	s_mov_b64 s[10:11], 0x400000
	s_mov_b64 s[18:19], 0x10000
	s_movk_i32 s26, 0x2000
	s_movk_i32 s27, 0x110
	s_mov_b32 s28, s74
	s_mov_b32 s98, s75
	s_branch .Lp6_dyn_decode_n

; template <class F> DI void for_tiles_st(int ntm, int ntn, const Sched& sc, F f) {
;     ...
;     const int nsn = ntn >> 3, nsuper = (ntm >> 3) * nsn;
;     for (int sp = sc.xd; sp < nsuper; sp += sc.nx) {
;       const int sm = sp / nsn, sn = sp - sm * nsn;
;       for (int qq = sc.rank; qq < 64; qq += sc.nloc) f(sm * 8 + (qq >> 3), sn * 8 + (qq & 7));
; DI void phase6(const Params& p, const Sched& sched, unsigned char* smem) {
;     ...
;     gemm_tile<8>((const u16*)(p.ws + OFF_WO), 1024, tn * 128, tm * 256, 1024, xl, [&](f32x4 (&acc)[4][8], int fb, int tb, int lr, int lq, int wf, int wt) {
.LBB0_811:
	v_readfirstlane_b32 s34, v218
	s_cmp_lg_u32 s34, 0
	s_cbranch_scc1 .Lp6_dyn_skip_a
	s_mov_b64 s[100:101], exec
	s_mov_b64 exec, 1
	v_mov_b32_e32 v241, 0x3fb04500
	v_lshl_add_u32 v241, s74, 6, v241
	v_mov_b32_e32 v242, 1
	global_atomic_add v240, v241, v242, s[42:43] sc0
	s_mov_b64 exec, s[100:101]

; DI f32x4 mfma16(bf16x8 a, bf16x8 b, f32x4 c) { return __builtin_amdgcn_mfma_f32_16x16x32_bf16(a, b, c, 0, 0, 0); }
; template <int NI, class XL, class EP>
; DI void gemm_tile(const u16* __restrict__ W, int ldw, int f0, int t0, int K, XL xl, EP ep, unsigned char* smem) {
;     ...
;   for (int it = 0; it < nk; ++it) {
;     const u16* Ws = S0 + (it & 1) * BUF; const u16* Xs = Ws + 128 * LST;
;     __builtin_amdgcn_s_setprio(1);
;     bf16x8 a[4];
; #pragma unroll
;     for (int mi = 0; mi < 4; ++mi) a[mi] = *(const bf16x8*)(Ws + (wf * 64 + mi * 16 + lr) * LST + lq * 8);
; #pragma unroll
;     for (int ni = 0; ni < NI; ++ni) {
;       const bf16x8 b = *(const bf16x8*)(Xs + (wt * (NI * 16) + ni * 16 + lr) * LST + lq * 8);
; #pragma unroll
;       for (int mi = 0; mi < 4; ++mi) acc[mi][ni] = mfma16(a[mi], b, acc[mi][ni]);
;     }
;     __builtin_amdgcn_sched_group_barrier(0x100, 6, 0);
; #pragma unroll
;     for (int ni = 0; ni < NI; ++ni) { __builtin_amdgcn_sched_group_barrier(0x008, 4, 0); if (ni + 2 < NI) __builtin_amdgcn_sched_group_barrier(0x100, 1, 0); }
;     __builtin_amdgcn_s_setprio(0);
;     if (it + 1 < nk) lstore((it + 1) & 1);
;     if (it + 2 < nk) gload(it + 2);
;     __syncthreads();
;   }
.LBB0_812:
	s_setprio 1
	ds_read_b128 v[168:171], v228 offset:0
	ds_read_b128 v[172:175], v228 offset:1536
	ds_read_b128 v[180:183], v228 offset:3072
	ds_read_b128 v[184:187], v228 offset:4608
	ds_read_b128 v[176:179], v152 offset:12288
	ds_read_b128 v[188:191], v152 offset:13824
	s_waitcnt lgkmcnt(1)
	v_mfma_f32_16x16x32_bf16 v[148:151], v[168:171], v[176:179], v[148:151]
	v_mfma_f32_16x16x32_bf16 v[136:139], v[172:175], v[176:179], v[136:139]
	v_mfma_f32_16x16x32_bf16 v[112:115], v[180:183], v[176:179], v[112:115]
	v_mfma_f32_16x16x32_bf16 v[80:83], v[184:187], v[176:179], v[80:83]
	ds_read_b128 v[176:179], v152 offset:15360
	s_waitcnt vmcnt(6)
	ds_write_b128 v229, v[20:23] offset:36864
	s_waitcnt lgkmcnt(2)
	v_mfma_f32_16x16x32_bf16 v[144:147], v[168:171], v[188:191], v[144:147]
	v_mfma_f32_16x16x32_bf16 v[128:131], v[172:175], v[188:191], v[128:131]
	v_mfma_f32_16x16x32_bf16 v[100:103], v[180:183], v[188:191], v[100:103]
	v_mfma_f32_16x16x32_bf16 v[68:71], v[184:187], v[188:191], v[68:71]
	ds_read_b128 v[188:191], v152 offset:16896
	ds_write_b128 v229, v[16:19] offset:36960
	global_load_dwordx4 v[20:23], v154, s[98:99]
	global_load_dwordx4 v[16:19], v154, s[98:99] offset:64
	s_waitcnt lgkmcnt(3)
	v_mfma_f32_16x16x32_bf16 v[140:143], v[168:171], v[176:179], v[140:143]
	v_mfma_f32_16x16x32_bf16 v[120:123], v[172:175], v[176:179], v[120:123]
	v_mfma_f32_16x16x32_bf16 v[88:91], v[180:183], v[176:179], v[88:91]
	v_mfma_f32_16x16x32_bf16 v[44:47], v[184:187], v[176:179], v[44:47]
	ds_read_b128 v[176:179], v152 offset:18432
	ds_write_b128 v230, v[36:39] offset:49152
	global_load_dwordx4 v[36:39], v156, s[100:101] offset:2048
	s_waitcnt lgkmcnt(3)
	v_mfma_f32_16x16x32_bf16 v[132:135], v[168:171], v[188:191], v[132:135]
	v_mfma_f32_16x16x32_bf16 v[108:111], v[172:175], v[188:191], v[108:111]
	v_mfma_f32_16x16x32_bf16 v[76:79], v[180:183], v[188:191], v[76:79]
	v_mfma_f32_16x16x32_bf16 v[40:43], v[184:187], v[188:191], v[40:43]
	ds_read_b128 v[188:191], v152 offset:19968
	ds_write_b128 v230, v[32:35] offset:49248
	global_load_dwordx4 v[32:35], v156, s[100:101] offset:2112
	s_waitcnt lgkmcnt(3)
	v_mfma_f32_16x16x32_bf16 v[124:127], v[168:171], v[176:179], v[124:127]
	v_mfma_f32_16x16x32_bf16 v[96:99], v[172:175], v[176:179], v[96:99]
	v_mfma_f32_16x16x32_bf16 v[64:67], v[180:183], v[176:179], v[64:67]
	v_mfma_f32_16x16x32_bf16 v[12:15], v[184:187], v[176:179], v[12:15]
	ds_read_b128 v[176:179], v152 offset:21504
	ds_write_b128 v230, v[28:31] offset:49344
	global_load_dwordx4 v[28:31], v156, s[100:101] offset:2176
	s_waitcnt lgkmcnt(3)
	v_mfma_f32_16x16x32_bf16 v[116:119], v[168:171], v[188:191], v[116:119]
	v_mfma_f32_16x16x32_bf16 v[84:87], v[172:175], v[188:191], v[84:87]
	v_mfma_f32_16x16x32_bf16 v[56:59], v[180:183], v[188:191], v[56:59]
	v_mfma_f32_16x16x32_bf16 v[8:11], v[184:187], v[188:191], v[8:11]
	ds_read_b128 v[188:191], v152 offset:23040
	ds_write_b128 v230, v[24:27] offset:49440
	global_load_dwordx4 v[24:27], v156, s[100:101] offset:2240
	s_waitcnt lgkmcnt(3)
	v_mfma_f32_16x16x32_bf16 v[104:107], v[168:171], v[176:179], v[104:107]
	v_mfma_f32_16x16x32_bf16 v[72:75], v[172:175], v[176:179], v[72:75]
	v_mfma_f32_16x16x32_bf16 v[52:55], v[180:183], v[176:179], v[52:55]
	v_mfma_f32_16x16x32_bf16 v[4:7], v[184:187], v[176:179], v[4:7]
	s_add_u32 s98, s98, s18
	s_addc_u32 s99, s99, s19
	s_add_u32 s100, s100, s10
	s_addc_u32 s101, s101, s11
	s_waitcnt lgkmcnt(1)
	v_mfma_f32_16x16x32_bf16 v[92:95], v[168:171], v[188:191], v[92:95]
	v_mfma_f32_16x16x32_bf16 v[60:63], v[172:175], v[188:191], v[60:63]
	v_mfma_f32_16x16x32_bf16 v[48:51], v[180:183], v[188:191], v[48:51]
	v_mfma_f32_16x16x32_bf16 v[0:3], v[184:187], v[188:191], v[0:3]
	s_setprio 0
	s_waitcnt lgkmcnt(0)
	s_barrier
	s_setprio 1
	ds_read_b128 v[168:171], v228 offset:36864
	ds_read_b128 v[172:175], v228 offset:38400
	ds_read_b128 v[180:183], v228 offset:39936
	ds_read_b128 v[184:187], v228 offset:41472
	ds_read_b128 v[176:179], v152 offset:49152
	ds_read_b128 v[188:191], v152 offset:50688
	s_waitcnt lgkmcnt(1)
	v_mfma_f32_16x16x32_bf16 v[148:151], v[168:171], v[176:179], v[148:151]
	v_mfma_f32_16x16x32_bf16 v[136:139], v[172:175], v[176:179], v[136:139]
	v_mfma_f32_16x16x32_bf16 v[112:115], v[180:183], v[176:179], v[112:115]
	v_mfma_f32_16x16x32_bf16 v[80:83], v[184:187], v[176:179], v[80:83]
	ds_read_b128 v[176:179], v152 offset:52224
	s_waitcnt vmcnt(6)
	ds_write_b128 v229, v[200:203] offset:0
	s_waitcnt lgkmcnt(2)
	v_mfma_f32_16x16x32_bf16 v[144:147], v[168:171], v[188:191], v[144:147]
	v_mfma_f32_16x16x32_bf16 v[128:131], v[172:175], v[188:191], v[128:131]
	v_mfma_f32_16x16x32_bf16 v[100:103], v[180:183], v[188:191], v[100:103]
	v_mfma_f32_16x16x32_bf16 v[68:71], v[184:187], v[188:191], v[68:71]
	ds_read_b128 v[188:191], v152 offset:53760
	ds_write_b128 v229, v[204:207] offset:96
	global_load_dwordx4 v[200:203], v154, s[98:99]
	global_load_dwordx4 v[204:207], v154, s[98:99] offset:64
	s_waitcnt lgkmcnt(3)
	v_mfma_f32_16x16x32_bf16 v[140:143], v[168:171], v[176:179], v[140:143]
	v_mfma_f32_16x16x32_bf16 v[120:123], v[172:175], v[176:179], v[120:123]
	v_mfma_f32_16x16x32_bf16 v[88:91], v[180:183], v[176:179], v[88:91]
	v_mfma_f32_16x16x32_bf16 v[44:47], v[184:187], v[176:179], v[44:47]
	ds_read_b128 v[176:179], v152 offset:55296
	ds_write_b128 v230, v[208:211] offset:12288
	global_load_dwordx4 v[208:211], v156, s[100:101] offset:2048
	s_waitcnt lgkmcnt(3)
; DI f32x4 mfma16(bf16x8 a, bf16x8 b, f32x4 c) { return __builtin_amdgcn_mfma_f32_16x16x32_bf16(a, b, c, 0, 0, 0); }
; template <int NI, class XL, class EP>
; DI void gemm_tile(const u16* __restrict__ W, int ldw, int f0, int t0, int K, XL xl, EP ep, unsigned char* smem) {
;     ...
;   for (int it = 0; it < nk; ++it) {
;     const u16* Ws = S0 + (it & 1) * BUF; const u16* Xs = Ws + 128 * LST;
;     __builtin_amdgcn_s_setprio(1);
;     bf16x8 a[4];
; #pragma unroll
;     for (int mi = 0; mi < 4; ++mi) a[mi] = *(const bf16x8*)(Ws + (wf * 64 + mi * 16 + lr) * LST + lq * 8);
; #pragma unroll
;     for (int ni = 0; ni < NI; ++ni) {
;       const bf16x8 b = *(const bf16x8*)(Xs + (wt * (NI * 16) + ni * 16 + lr) * LST + lq * 8);
; #pragma unroll
;       for (int mi = 0; mi < 4; ++mi) acc[mi][ni] = mfma16(a[mi], b, acc[mi][ni]);
;     }
;     __builtin_amdgcn_sched_group_barrier(0x100, 6, 0);
; #pragma unroll
;     for (int ni = 0; ni < NI; ++ni) { __builtin_amdgcn_sched_group_barrier(0x008, 4, 0); if (ni + 2 < NI) __builtin_amdgcn_sched_group_barrier(0x100, 1, 0); }
;     __builtin_amdgcn_s_setprio(0);
;     if (it + 1 < nk) lstore((it + 1) & 1);
;     if (it + 2 < nk) gload(it + 2);
;     __syncthreads();
;   }
	v_mfma_f32_16x16x32_bf16 v[132:135], v[168:171], v[188:191], v[132:135]
	v_mfma_f32_16x16x32_bf16 v[108:111], v[172:175], v[188:191], v[108:111]
	v_mfma_f32_16x16x32_bf16 v[76:79], v[180:183], v[188:191], v[76:79]
	v_mfma_f32_16x16x32_bf16 v[40:43], v[184:187], v[188:191], v[40:43]
	ds_read_b128 v[188:191], v152 offset:56832
	ds_write_b128 v230, v[212:215] offset:12384
	global_load_dwordx4 v[212:215], v156, s[100:101] offset:2112
	s_waitcnt lgkmcnt(3)
	v_mfma_f32_16x16x32_bf16 v[124:127], v[168:171], v[176:179], v[124:127]
	v_mfma_f32_16x16x32_bf16 v[96:99], v[172:175], v[176:179], v[96:99]
	v_mfma_f32_16x16x32_bf16 v[64:67], v[180:183], v[176:179], v[64:67]
	v_mfma_f32_16x16x32_bf16 v[12:15], v[184:187], v[176:179], v[12:15]
	ds_read_b128 v[176:179], v152 offset:58368
	ds_write_b128 v230, v[220:223] offset:12480
	global_load_dwordx4 v[220:223], v156, s[100:101] offset:2176
	s_waitcnt lgkmcnt(3)
	v_mfma_f32_16x16x32_bf16 v[116:119], v[168:171], v[188:191], v[116:119]
	v_mfma_f32_16x16x32_bf16 v[84:87], v[172:175], v[188:191], v[84:87]
	v_mfma_f32_16x16x32_bf16 v[56:59], v[180:183], v[188:191], v[56:59]
	v_mfma_f32_16x16x32_bf16 v[8:11], v[184:187], v[188:191], v[8:11]
	ds_read_b128 v[188:191], v152 offset:59904
	ds_write_b128 v230, v[224:227] offset:12576
	global_load_dwordx4 v[224:227], v156, s[100:101] offset:2240
	s_waitcnt lgkmcnt(3)
	v_mfma_f32_16x16x32_bf16 v[104:107], v[168:171], v[176:179], v[104:107]
	v_mfma_f32_16x16x32_bf16 v[72:75], v[172:175], v[176:179], v[72:75]
	v_mfma_f32_16x16x32_bf16 v[52:55], v[180:183], v[176:179], v[52:55]
	v_mfma_f32_16x16x32_bf16 v[4:7], v[184:187], v[176:179], v[4:7]
	s_add_u32 s98, s98, s18
	s_addc_u32 s99, s99, s19
	s_add_u32 s100, s100, s10
	s_addc_u32 s101, s101, s11
	s_add_i32 s36, s36, 2
	s_waitcnt lgkmcnt(1)
	v_mfma_f32_16x16x32_bf16 v[92:95], v[168:171], v[188:191], v[92:95]
	v_mfma_f32_16x16x32_bf16 v[60:63], v[172:175], v[188:191], v[60:63]
	v_mfma_f32_16x16x32_bf16 v[48:51], v[180:183], v[188:191], v[48:51]
	v_mfma_f32_16x16x32_bf16 v[0:3], v[184:187], v[188:191], v[0:3]
	s_setprio 0
	s_cmp_lg_u32 s36, 29
	s_waitcnt lgkmcnt(0)
	s_barrier
	s_cbranch_scc1 .LBB0_812
	s_setprio 1
	ds_read_b128 v[168:171], v228 offset:0
	ds_read_b128 v[172:175], v228 offset:1536
	ds_read_b128 v[180:183], v228 offset:3072
	ds_read_b128 v[184:187], v228 offset:4608
	ds_read_b128 v[176:179], v152 offset:12288
	ds_read_b128 v[188:191], v152 offset:13824
	s_waitcnt lgkmcnt(1)
	v_mfma_f32_16x16x32_bf16 v[148:151], v[168:171], v[176:179], v[148:151]
	v_mfma_f32_16x16x32_bf16 v[136:139], v[172:175], v[176:179], v[136:139]
	v_mfma_f32_16x16x32_bf16 v[112:115], v[180:183], v[176:179], v[112:115]
	v_mfma_f32_16x16x32_bf16 v[80:83], v[184:187], v[176:179], v[80:83]
	ds_read_b128 v[176:179], v152 offset:15360
	s_waitcnt vmcnt(6)
	ds_write_b128 v229, v[20:23] offset:36864
	s_waitcnt lgkmcnt(2)
	v_mfma_f32_16x16x32_bf16 v[144:147], v[168:171], v[188:191], v[144:147]
	v_mfma_f32_16x16x32_bf16 v[128:131], v[172:175], v[188:191], v[128:131]
	v_mfma_f32_16x16x32_bf16 v[100:103], v[180:183], v[188:191], v[100:103]
	v_mfma_f32_16x16x32_bf16 v[68:71], v[184:187], v[188:191], v[68:71]
	ds_read_b128 v[188:191], v152 offset:16896
	ds_write_b128 v229, v[16:19] offset:36960
	global_load_dwordx4 v[20:23], v154, s[98:99]
	global_load_dwordx4 v[16:19], v154, s[98:99] offset:64
	s_waitcnt lgkmcnt(3)
	v_mfma_f32_16x16x32_bf16 v[140:143], v[168:171], v[176:179], v[140:143]
	v_mfma_f32_16x16x32_bf16 v[120:123], v[172:175], v[176:179], v[120:123]
	v_mfma_f32_16x16x32_bf16 v[88:91], v[180:183], v[176:179], v[88:91]
	v_mfma_f32_16x16x32_bf16 v[44:47], v[184:187], v[176:179], v[44:47]
	ds_read_b128 v[176:179], v152 offset:18432
	ds_write_b128 v230, v[36:39] offset:49152
	global_load_dwordx4 v[36:39], v156, s[100:101] offset:2048
	s_waitcnt lgkmcnt(3)
	v_mfma_f32_16x16x32_bf16 v[132:135], v[168:171], v[188:191], v[132:135]
	v_mfma_f32_16x16x32_bf16 v[108:111], v[172:175], v[188:191], v[108:111]
	v_mfma_f32_16x16x32_bf16 v[76:79], v[180:183], v[188:191], v[76:79]
	v_mfma_f32_16x16x32_bf16 v[40:43], v[184:187], v[188:191], v[40:43]
	ds_read_b128 v[188:191], v152 offset:19968
	ds_write_b128 v230, v[32:35] offset:49248
	global_load_dwordx4 v[32:35], v156, s[100:101] offset:2112
	s_waitcnt lgkmcnt(3)
	v_mfma_f32_16x16x32_bf16 v[124:127], v[168:171], v[176:179], v[124:127]
	v_mfma_f32_16x16x32_bf16 v[96:99], v[172:175], v[176:179], v[96:99]
	v_mfma_f32_16x16x32_bf16 v[64:67], v[180:183], v[176:179], v[64:67]
	v_mfma_f32_16x16x32_bf16 v[12:15], v[184:187], v[176:179], v[12:15]
	ds_read_b128 v[176:179], v152 offset:21504
	ds_write_b128 v230, v[28:31] offset:49344
	global_load_dwordx4 v[28:31], v156, s[100:101] offset:2176
	s_waitcnt lgkmcnt(3)
	v_mfma_f32_16x16x32_bf16 v[116:119], v[168:171], v[188:191], v[116:119]
	v_mfma_f32_16x16x32_bf16 v[84:87], v[172:175], v[188:191], v[84:87]
	v_mfma_f32_16x16x32_bf16 v[56:59], v[180:183], v[188:191], v[56:59]
	v_mfma_f32_16x16x32_bf16 v[8:11], v[184:187], v[188:191], v[8:11]
	ds_read_b128 v[188:191], v152 offset:23040
	ds_write_b128 v230, v[24:27] offset:49440
	global_load_dwordx4 v[24:27], v156, s[100:101] offset:2240
	s_waitcnt lgkmcnt(3)
	v_mfma_f32_16x16x32_bf16 v[104:107], v[168:171], v[176:179], v[104:107]
	v_mfma_f32_16x16x32_bf16 v[72:75], v[172:175], v[176:179], v[72:75]
	v_mfma_f32_16x16x32_bf16 v[52:55], v[180:183], v[176:179], v[52:55]
	v_mfma_f32_16x16x32_bf16 v[4:7], v[184:187], v[176:179], v[4:7]
	s_add_u32 s98, s98, s18
	s_addc_u32 s99, s99, s19
	s_add_u32 s100, s100, s10
	s_addc_u32 s101, s101, s11
	s_waitcnt lgkmcnt(1)
	v_mfma_f32_16x16x32_bf16 v[92:95], v[168:171], v[188:191], v[92:95]
	v_mfma_f32_16x16x32_bf16 v[60:63], v[172:175], v[188:191], v[60:63]
	v_mfma_f32_16x16x32_bf16 v[48:51], v[180:183], v[188:191], v[48:51]
	v_mfma_f32_16x16x32_bf16 v[0:3], v[184:187], v[188:191], v[0:3]
	s_setprio 0
	s_waitcnt lgkmcnt(0)
	s_barrier
; DI f32x4 mfma16(bf16x8 a, bf16x8 b, f32x4 c) { return __builtin_amdgcn_mfma_f32_16x16x32_bf16(a, b, c, 0, 0, 0); }
; template <int NI, class XL, class EP>
; DI void gemm_tile(const u16* __restrict__ W, int ldw, int f0, int t0, int K, XL xl, EP ep, unsigned char* smem) {
;     ...
;   for (int it = 0; it < nk; ++it) {
;     const u16* Ws = S0 + (it & 1) * BUF; const u16* Xs = Ws + 128 * LST;
;     __builtin_amdgcn_s_setprio(1);
;     bf16x8 a[4];
; #pragma unroll
;     for (int mi = 0; mi < 4; ++mi) a[mi] = *(const bf16x8*)(Ws + (wf * 64 + mi * 16 + lr) * LST + lq * 8);
; #pragma unroll
;     for (int ni = 0; ni < NI; ++ni) {
;       const bf16x8 b = *(const bf16x8*)(Xs + (wt * (NI * 16) + ni * 16 + lr) * LST + lq * 8);
; #pragma unroll
;       for (int mi = 0; mi < 4; ++mi) acc[mi][ni] = mfma16(a[mi], b, acc[mi][ni]);
;     }
;     __builtin_amdgcn_sched_group_barrier(0x100, 6, 0);
; #pragma unroll
;     for (int ni = 0; ni < NI; ++ni) { __builtin_amdgcn_sched_group_barrier(0x008, 4, 0); if (ni + 2 < NI) __builtin_amdgcn_sched_group_barrier(0x100, 1, 0); }
;     __builtin_amdgcn_s_setprio(0);
;     if (it + 1 < nk) lstore((it + 1) & 1);
;     if (it + 2 < nk) gload(it + 2);
;     __syncthreads();
;   }
	s_setprio 1
	ds_read_b128 v[168:171], v228 offset:36864
	ds_read_b128 v[172:175], v228 offset:38400
	ds_read_b128 v[180:183], v228 offset:39936
	ds_read_b128 v[184:187], v228 offset:41472
	ds_read_b128 v[176:179], v152 offset:49152
	ds_read_b128 v[188:191], v152 offset:50688
	s_waitcnt lgkmcnt(1)
	v_mfma_f32_16x16x32_bf16 v[148:151], v[168:171], v[176:179], v[148:151]
	v_mfma_f32_16x16x32_bf16 v[136:139], v[172:175], v[176:179], v[136:139]
	v_mfma_f32_16x16x32_bf16 v[112:115], v[180:183], v[176:179], v[112:115]
	v_mfma_f32_16x16x32_bf16 v[80:83], v[184:187], v[176:179], v[80:83]
	ds_read_b128 v[176:179], v152 offset:52224
	s_waitcnt vmcnt(6)
	ds_write_b128 v229, v[200:203] offset:0
	s_waitcnt lgkmcnt(2)
	v_mfma_f32_16x16x32_bf16 v[144:147], v[168:171], v[188:191], v[144:147]
	v_mfma_f32_16x16x32_bf16 v[128:131], v[172:175], v[188:191], v[128:131]
	v_mfma_f32_16x16x32_bf16 v[100:103], v[180:183], v[188:191], v[100:103]
	v_mfma_f32_16x16x32_bf16 v[68:71], v[184:187], v[188:191], v[68:71]
	ds_read_b128 v[188:191], v152 offset:53760
	ds_write_b128 v229, v[204:207] offset:96
	s_waitcnt lgkmcnt(3)
	v_mfma_f32_16x16x32_bf16 v[140:143], v[168:171], v[176:179], v[140:143]
	v_mfma_f32_16x16x32_bf16 v[120:123], v[172:175], v[176:179], v[120:123]
	v_mfma_f32_16x16x32_bf16 v[88:91], v[180:183], v[176:179], v[88:91]
	v_mfma_f32_16x16x32_bf16 v[44:47], v[184:187], v[176:179], v[44:47]
	ds_read_b128 v[176:179], v152 offset:55296
	ds_write_b128 v230, v[208:211] offset:12288
	s_waitcnt lgkmcnt(3)
	v_mfma_f32_16x16x32_bf16 v[132:135], v[168:171], v[188:191], v[132:135]
	v_mfma_f32_16x16x32_bf16 v[108:111], v[172:175], v[188:191], v[108:111]
	v_mfma_f32_16x16x32_bf16 v[76:79], v[180:183], v[188:191], v[76:79]
	v_mfma_f32_16x16x32_bf16 v[40:43], v[184:187], v[188:191], v[40:43]
	ds_read_b128 v[188:191], v152 offset:56832
	ds_write_b128 v230, v[212:215] offset:12384
	s_waitcnt lgkmcnt(3)
	v_mfma_f32_16x16x32_bf16 v[124:127], v[168:171], v[176:179], v[124:127]
	v_mfma_f32_16x16x32_bf16 v[96:99], v[172:175], v[176:179], v[96:99]
	v_mfma_f32_16x16x32_bf16 v[64:67], v[180:183], v[176:179], v[64:67]
	v_mfma_f32_16x16x32_bf16 v[12:15], v[184:187], v[176:179], v[12:15]
	ds_read_b128 v[176:179], v152 offset:58368
	ds_write_b128 v230, v[220:223] offset:12480
	s_waitcnt lgkmcnt(3)
	v_mfma_f32_16x16x32_bf16 v[116:119], v[168:171], v[188:191], v[116:119]
	v_mfma_f32_16x16x32_bf16 v[84:87], v[172:175], v[188:191], v[84:87]
	v_mfma_f32_16x16x32_bf16 v[56:59], v[180:183], v[188:191], v[56:59]
	v_mfma_f32_16x16x32_bf16 v[8:11], v[184:187], v[188:191], v[8:11]
	ds_read_b128 v[188:191], v152 offset:59904
	ds_write_b128 v230, v[224:227] offset:12576
	s_waitcnt lgkmcnt(3)
	v_mfma_f32_16x16x32_bf16 v[104:107], v[168:171], v[176:179], v[104:107]
	v_mfma_f32_16x16x32_bf16 v[72:75], v[172:175], v[176:179], v[72:75]
	v_mfma_f32_16x16x32_bf16 v[52:55], v[180:183], v[176:179], v[52:55]
	v_mfma_f32_16x16x32_bf16 v[4:7], v[184:187], v[176:179], v[4:7]
	s_add_i32 s36, s36, 2
	s_waitcnt lgkmcnt(1)
	v_mfma_f32_16x16x32_bf16 v[92:95], v[168:171], v[188:191], v[92:95]
	v_mfma_f32_16x16x32_bf16 v[60:63], v[172:175], v[188:191], v[60:63]
	v_mfma_f32_16x16x32_bf16 v[48:51], v[180:183], v[188:191], v[48:51]
	v_mfma_f32_16x16x32_bf16 v[0:3], v[184:187], v[188:191], v[0:3]
	s_setprio 0
	s_waitcnt lgkmcnt(0)
	s_barrier
	s_setprio 1
	v_lshl_add_u32 v152, v167, 1, v164
	ds_read_b128 v[154:157], v152
	v_lshl_add_u32 v161, v165, 1, v164
	ds_read_b128 v[164:167], v152 offset:1536
	ds_read_b128 v[172:175], v152 offset:3072
	ds_read_b128 v[176:179], v152 offset:4608
	ds_read_b128 v[168:171], v161 offset:12288
	ds_read_b128 v[180:183], v161 offset:13824
	s_waitcnt lgkmcnt(1)
	v_mfma_f32_16x16x32_bf16 v[148:151], v[154:157], v[168:171], v[148:151]
	v_mfma_f32_16x16x32_bf16 v[136:139], v[164:167], v[168:171], v[136:139]
	v_mfma_f32_16x16x32_bf16 v[112:115], v[172:175], v[168:171], v[112:115]
	v_mfma_f32_16x16x32_bf16 v[80:83], v[176:179], v[168:171], v[80:83]
	ds_read_b128 v[168:171], v161 offset:15360
	s_waitcnt vmcnt(5)
	ds_write_b128 v162, v[20:23] offset:36864
	s_waitcnt lgkmcnt(2)
	v_mfma_f32_16x16x32_bf16 v[144:147], v[154:157], v[180:183], v[144:147]
	v_mfma_f32_16x16x32_bf16 v[128:131], v[164:167], v[180:183], v[128:131]
	v_mfma_f32_16x16x32_bf16 v[100:103], v[172:175], v[180:183], v[100:103]
	v_mfma_f32_16x16x32_bf16 v[68:71], v[176:179], v[180:183], v[68:71]
	ds_read_b128 v[180:183], v161 offset:16896
	s_waitcnt vmcnt(4)
	ds_write_b128 v162, v[16:19] offset:36960
	s_waitcnt lgkmcnt(3)
	v_mfma_f32_16x16x32_bf16 v[140:143], v[154:157], v[168:171], v[140:143]
	v_mfma_f32_16x16x32_bf16 v[120:123], v[164:167], v[168:171], v[120:123]
	v_mfma_f32_16x16x32_bf16 v[184:187], v[172:175], v[168:171], v[88:91]
	v_mfma_f32_16x16x32_bf16 v[44:47], v[176:179], v[168:171], v[44:47]
	s_nop 1
	ds_read_b128 v[88:91], v161 offset:18432
	s_waitcnt vmcnt(3)
	ds_write_b128 v163, v[36:39] offset:49152
	s_waitcnt lgkmcnt(3)
	v_mfma_f32_16x16x32_bf16 v[132:135], v[154:157], v[180:183], v[132:135]
	v_mfma_f32_16x16x32_bf16 v[168:171], v[164:167], v[180:183], v[108:111]
	v_mfma_f32_16x16x32_bf16 v[188:191], v[172:175], v[180:183], v[76:79]
	v_mfma_f32_16x16x32_bf16 v[180:183], v[176:179], v[180:183], v[40:43]
	s_nop 2
	ds_read_b128 v[40:43], v161 offset:19968
	s_waitcnt vmcnt(2)
	ds_write_b128 v163, v[32:35] offset:49248
	s_waitcnt lgkmcnt(3)
	v_mfma_f32_16x16x32_bf16 v[124:127], v[154:157], v[88:91], v[124:127]
	v_mfma_f32_16x16x32_bf16 v[192:195], v[164:167], v[88:91], v[96:99]
	v_mfma_f32_16x16x32_bf16 v[196:199], v[172:175], v[88:91], v[64:67]
	v_mfma_f32_16x16x32_bf16 v[200:203], v[176:179], v[88:91], v[12:15]
	s_nop 2
	ds_read_b128 v[12:15], v161 offset:21504
	s_waitcnt vmcnt(1)
	ds_write_b128 v163, v[28:31] offset:49344
	s_waitcnt lgkmcnt(3)
	v_mfma_f32_16x16x32_bf16 v[116:119], v[154:157], v[40:43], v[116:119]
	v_mfma_f32_16x16x32_bf16 v[204:207], v[164:167], v[40:43], v[84:87]
	v_mfma_f32_16x16x32_bf16 v[56:59], v[172:175], v[40:43], v[56:59]
	v_mfma_f32_16x16x32_bf16 v[208:211], v[176:179], v[40:43], v[8:11]
	s_nop 2
	ds_read_b128 v[8:11], v161 offset:23040
	s_waitcnt vmcnt(0)
	ds_write_b128 v163, v[24:27] offset:49440
	s_waitcnt lgkmcnt(3)
	v_mfma_f32_16x16x32_bf16 v[212:215], v[154:157], v[12:15], v[104:107]
	v_mfma_f32_16x16x32_bf16 v[72:75], v[164:167], v[12:15], v[72:75]
	v_mfma_f32_16x16x32_bf16 v[220:223], v[172:175], v[12:15], v[52:55]
	v_mfma_f32_16x16x32_bf16 v[224:227], v[176:179], v[12:15], v[4:7]
	s_waitcnt lgkmcnt(1)
	v_mfma_f32_16x16x32_bf16 v[154:157], v[154:157], v[8:11], v[92:95]
	v_mfma_f32_16x16x32_bf16 v[60:63], v[164:167], v[8:11], v[60:63]
	v_mfma_f32_16x16x32_bf16 v[164:167], v[172:175], v[8:11], v[48:51]
	v_mfma_f32_16x16x32_bf16 v[172:175], v[176:179], v[8:11], v[0:3]
	s_setprio 0
	s_waitcnt lgkmcnt(0)
	s_barrier
; DI void store4(u16* dst, f32x4 v) { uint2 w; w.x = cvtpk(v[0], v[1]); w.y = cvtpk(v[2], v[3]); *(uint2*)dst = w; }
; DI void phase6(const Params& p, const Sched& sched, unsigned char* smem) {
;     ...
;       constexpr int EST = 136;
;       u16* Ls = (u16*)smem;
;       const int b = tb >> 11;
;       __syncthreads();
; #pragma unroll
;       for (int mi = 0; mi < 4; ++mi) {
;         const int f = fb + mi * 16 + lq * 4; const float4 gm = *(const float4*)(mod + (size_t)b * 6144 + 2048 + f);
; #pragma unroll
;         for (int ni = 0; ni < 8; ++ni) {
;           const f32x4 o = {gm.x * acc[mi][ni][0], gm.y * acc[mi][ni][1], gm.z * acc[mi][ni][2], gm.w * acc[mi][ni][3]};
;           store4(Ls + (wt * 128 + ni * 16 + lr) * EST + wf * 64 + mi * 16 + lq * 4, o);
;         }
;       }
	s_lshl_b32 s34, s34, 7
	s_setprio 1
	ds_read_b128 v[28:31], v152 offset:36864
	ds_read_b128 v[176:179], v152 offset:38400
	ds_read_b128 v[228:231], v152 offset:39936
	ds_read_b128 v[232:235], v152 offset:41472
	ds_read_b128 v[0:3], v161 offset:49152
	ds_read_b128 v[4:7], v161 offset:50688
	s_waitcnt lgkmcnt(1)
	v_mfma_f32_16x16x32_bf16 v[88:91], v[28:31], v[0:3], v[148:151]
	v_mfma_f32_16x16x32_bf16 v[64:67], v[176:179], v[0:3], v[136:139]
	v_mfma_f32_16x16x32_bf16 v[32:35], v[228:231], v[0:3], v[112:115]
	v_mfma_f32_16x16x32_bf16 v[0:3], v[232:235], v[0:3], v[80:83]
	ds_read_b128 v[8:11], v161 offset:52224
	s_waitcnt lgkmcnt(1)
	v_mfma_f32_16x16x32_bf16 v[96:99], v[28:31], v[4:7], v[144:147]
	v_mfma_f32_16x16x32_bf16 v[76:79], v[176:179], v[4:7], v[128:131]
	v_mfma_f32_16x16x32_bf16 v[36:39], v[228:231], v[4:7], v[100:103]
	v_mfma_f32_16x16x32_bf16 v[4:7], v[232:235], v[4:7], v[68:71]
	ds_read_b128 v[12:15], v161 offset:53760
	s_waitcnt lgkmcnt(1)
	v_mfma_f32_16x16x32_bf16 v[104:107], v[28:31], v[8:11], v[140:143]
	v_mfma_f32_16x16x32_bf16 v[84:87], v[176:179], v[8:11], v[120:123]
	v_mfma_f32_16x16x32_bf16 v[40:43], v[228:231], v[8:11], v[184:187]
	v_mfma_f32_16x16x32_bf16 v[8:11], v[232:235], v[8:11], v[44:47]
	ds_read_b128 v[16:19], v161 offset:55296
	s_waitcnt lgkmcnt(1)
	v_mfma_f32_16x16x32_bf16 v[108:111], v[28:31], v[12:15], v[132:135]
	v_mfma_f32_16x16x32_bf16 v[92:95], v[176:179], v[12:15], v[168:171]
	v_mfma_f32_16x16x32_bf16 v[44:47], v[228:231], v[12:15], v[188:191]
	v_mfma_f32_16x16x32_bf16 v[12:15], v[232:235], v[12:15], v[180:183]
	ds_read_b128 v[20:23], v161 offset:56832
	s_waitcnt lgkmcnt(1)
	v_mfma_f32_16x16x32_bf16 v[112:115], v[28:31], v[16:19], v[124:127]
	v_mfma_f32_16x16x32_bf16 v[100:103], v[176:179], v[16:19], v[192:195]
	v_mfma_f32_16x16x32_bf16 v[48:51], v[228:231], v[16:19], v[196:199]
	v_mfma_f32_16x16x32_bf16 v[16:19], v[232:235], v[16:19], v[200:203]
	ds_read_b128 v[24:27], v161 offset:58368
	s_waitcnt lgkmcnt(1)
	v_mfma_f32_16x16x32_bf16 v[116:119], v[28:31], v[20:23], v[116:119]
	v_mfma_f32_16x16x32_bf16 v[68:71], v[176:179], v[20:23], v[204:207]
	v_mfma_f32_16x16x32_bf16 v[52:55], v[228:231], v[20:23], v[56:59]
	v_mfma_f32_16x16x32_bf16 v[20:23], v[232:235], v[20:23], v[208:211]
	ds_read_b128 v[128:131], v161 offset:59904
	s_waitcnt lgkmcnt(1)
	v_mfma_f32_16x16x32_bf16 v[120:123], v[28:31], v[24:27], v[212:215]
	v_mfma_f32_16x16x32_bf16 v[80:83], v[176:179], v[24:27], v[72:75]
	v_mfma_f32_16x16x32_bf16 v[56:59], v[228:231], v[24:27], v[220:223]
	v_mfma_f32_16x16x32_bf16 v[24:27], v[232:235], v[24:27], v[224:227]
	s_waitcnt lgkmcnt(0)
	v_mfma_f32_16x16x32_bf16 v[124:127], v[28:31], v[128:131], v[154:157]
	v_mfma_f32_16x16x32_bf16 v[72:75], v[176:179], v[128:131], v[60:63]
	v_mfma_f32_16x16x32_bf16 v[60:63], v[228:231], v[128:131], v[164:167]
	v_mfma_f32_16x16x32_bf16 v[28:31], v[232:235], v[128:131], v[172:175]
	s_setprio 0
	s_ashr_i32 s35, s35, 3
	v_add_u32_e32 v128, s34, v160
	s_mul_hi_i32 s37, s35, 0x6000
	s_mulk_i32 s35, 0x6000
	v_lshl_or_b32 v128, v158, 2, v128
	s_add_u32 s36, s72, s35
	s_addc_u32 s37, s73, s37
	v_ashrrev_i32_e32 v129, 31, v128
	v_lshl_add_u64 v[128:129], v[128:129], 2, s[36:37]
	v_add_co_u32_e32 v140, vcc, s26, v128
	v_mul_u32_u24_e32 v138, 0x88, v159
	s_nop 0
	v_addc_co_u32_e32 v141, vcc, 0, v129, vcc
	v_lshlrev_b32_e32 v136, 1, v160
	v_lshlrev_b32_e32 v137, 3, v158
	v_lshlrev_b32_e32 v138, 1, v138
	s_barrier
	global_load_dwordx4 v[128:131], v[140:141], off
	global_load_dwordx4 v[132:135], v[140:141], off offset:64
	v_add3_u32 v144, v136, v137, v138
	global_load_dwordx4 v[136:139], v[140:141], off offset:128
	v_add_u32_e32 v145, 0x1000, v144
	global_load_dwordx4 v[140:143], v[140:141], off offset:192
	v_add_u32_e32 v146, 0x2000, v144
	v_add_u32_e32 v147, 0x3000, v144
	v_add_u32_e32 v148, 0x4000, v144
	s_waitcnt vmcnt(3)
	v_pk_mul_f32 v[88:89], v[88:89], v[128:129]
	v_pk_mul_f32 v[90:91], v[90:91], v[130:131]
	v_pk_mul_f32 v[96:97], v[96:97], v[128:129]
	s_waitcnt vmcnt(1)
	v_pk_mul_f32 v[32:33], v[32:33], v[136:137]
	v_pk_mul_f32 v[34:35], v[34:35], v[138:139]
	s_waitcnt vmcnt(0)
	v_pk_mul_f32 v[0:1], v[0:1], v[140:141]
	v_pk_mul_f32 v[2:3], v[2:3], v[142:143]
	v_cvt_pk_bf16_f32 v32, v32, v33
	v_cvt_pk_bf16_f32 v33, v34, v35
	v_cvt_pk_bf16_f32 v0, v0, v1
	v_cvt_pk_bf16_f32 v1, v2, v3
	v_pk_mul_f32 v[34:35], v[36:37], v[136:137]
	v_pk_mul_f32 v[36:37], v[38:39], v[138:139]
	ds_write2_b64 v144, v[32:33], v[0:1] offset0:8 offset1:12
	v_pk_mul_f32 v[0:1], v[4:5], v[140:141]
	v_pk_mul_f32 v[2:3], v[6:7], v[142:143]
	v_cvt_pk_bf16_f32 v34, v34, v35
	v_cvt_pk_bf16_f32 v35, v36, v37
	v_cvt_pk_bf16_f32 v0, v0, v1
	v_cvt_pk_bf16_f32 v1, v2, v3
	v_pk_mul_f32 v[36:37], v[40:41], v[136:137]
	v_pk_mul_f32 v[38:39], v[42:43], v[138:139]
	ds_write2_b64 v145, v[34:35], v[0:1] offset0:40 offset1:44
	v_pk_mul_f32 v[0:1], v[8:9], v[140:141]
	v_pk_mul_f32 v[2:3], v[10:11], v[142:143]
	v_cvt_pk_bf16_f32 v36, v36, v37
	v_cvt_pk_bf16_f32 v37, v38, v39
	v_cvt_pk_bf16_f32 v0, v0, v1
	v_cvt_pk_bf16_f32 v1, v2, v3
	v_pk_mul_f32 v[38:39], v[44:45], v[136:137]
	v_pk_mul_f32 v[40:41], v[46:47], v[138:139]
	ds_write2_b64 v146, v[36:37], v[0:1] offset0:72 offset1:76
	v_pk_mul_f32 v[0:1], v[12:13], v[140:141]
	v_pk_mul_f32 v[2:3], v[14:15], v[142:143]
	v_cvt_pk_bf16_f32 v38, v38, v39
	v_cvt_pk_bf16_f32 v39, v40, v41
	v_cvt_pk_bf16_f32 v0, v0, v1
	v_cvt_pk_bf16_f32 v1, v2, v3
	v_pk_mul_f32 v[98:99], v[98:99], v[130:131]
	v_pk_mul_f32 v[64:65], v[64:65], v[132:133]
	v_pk_mul_f32 v[66:67], v[66:67], v[134:135]
	v_pk_mul_f32 v[76:77], v[76:77], v[132:133]
	v_pk_mul_f32 v[78:79], v[78:79], v[134:135]
; DI void store4(u16* dst, f32x4 v) { uint2 w; w.x = cvtpk(v[0], v[1]); w.y = cvtpk(v[2], v[3]); *(uint2*)dst = w; }
; DI void phase6(const Params& p, const Sched& sched, unsigned char* smem) {
;     ...
; #pragma unroll
;       for (int mi = 0; mi < 4; ++mi) {
;         const int f = fb + mi * 16 + lq * 4; const float4 gm = *(const float4*)(mod + (size_t)b * 6144 + 2048 + f);
; #pragma unroll
;         for (int ni = 0; ni < 8; ++ni) {
;           const f32x4 o = {gm.x * acc[mi][ni][0], gm.y * acc[mi][ni][1], gm.z * acc[mi][ni][2], gm.w * acc[mi][ni][3]};
;           store4(Ls + (wt * 128 + ni * 16 + lr) * EST + wf * 64 + mi * 16 + lq * 4, o);
;         }
;       }
;       __syncthreads();
	v_pk_mul_f32 v[40:41], v[48:49], v[136:137]
	v_pk_mul_f32 v[42:43], v[50:51], v[138:139]
	ds_write2_b64 v147, v[38:39], v[0:1] offset0:104 offset1:108
	v_pk_mul_f32 v[0:1], v[16:17], v[140:141]
	v_pk_mul_f32 v[2:3], v[18:19], v[142:143]
	v_cvt_pk_bf16_f32 v88, v88, v89
	v_cvt_pk_bf16_f32 v89, v90, v91
	v_cvt_pk_bf16_f32 v90, v96, v97
	v_cvt_pk_bf16_f32 v91, v98, v99
	v_cvt_pk_bf16_f32 v64, v64, v65
	v_cvt_pk_bf16_f32 v65, v66, v67
	v_cvt_pk_bf16_f32 v66, v76, v77
	v_cvt_pk_bf16_f32 v67, v78, v79
	v_cvt_pk_bf16_f32 v40, v40, v41
	v_cvt_pk_bf16_f32 v41, v42, v43
	v_cvt_pk_bf16_f32 v0, v0, v1
	v_cvt_pk_bf16_f32 v1, v2, v3
	v_pk_mul_f32 v[106:107], v[106:107], v[130:131]
	v_pk_mul_f32 v[116:117], v[116:117], v[128:129]
	v_pk_mul_f32 v[118:119], v[118:119], v[130:131]
	ds_write2_b64 v144, v[88:89], v[64:65] offset1:4
	ds_write2_b64 v145, v[90:91], v[66:67] offset0:32 offset1:36
	v_pk_mul_f32 v[64:65], v[68:69], v[132:133]
	v_pk_mul_f32 v[66:67], v[70:71], v[134:135]
	v_pk_mul_f32 v[42:43], v[52:53], v[136:137]
	v_pk_mul_f32 v[44:45], v[54:55], v[138:139]
	ds_write2_b64 v148, v[40:41], v[0:1] offset0:136 offset1:140
	v_pk_mul_f32 v[0:1], v[20:21], v[140:141]
	v_pk_mul_f32 v[2:3], v[22:23], v[142:143]
	v_cvt_pk_bf16_f32 v97, v106, v107
	v_cvt_pk_bf16_f32 v106, v116, v117
	v_cvt_pk_bf16_f32 v107, v118, v119
	v_cvt_pk_bf16_f32 v64, v64, v65
	v_cvt_pk_bf16_f32 v65, v66, v67
	v_add_u32_e32 v68, 0x5000, v144
	v_cvt_pk_bf16_f32 v42, v42, v43
	v_cvt_pk_bf16_f32 v43, v44, v45
	v_cvt_pk_bf16_f32 v0, v0, v1
	v_cvt_pk_bf16_f32 v1, v2, v3
	v_pk_mul_f32 v[108:109], v[108:109], v[128:129]
	v_pk_mul_f32 v[120:121], v[120:121], v[128:129]
	v_pk_mul_f32 v[122:123], v[122:123], v[130:131]
	ds_write2_b64 v68, v[106:107], v[64:65] offset0:160 offset1:164
	v_pk_mul_f32 v[64:65], v[80:81], v[132:133]
	v_pk_mul_f32 v[66:67], v[82:83], v[134:135]
	v_pk_mul_f32 v[44:45], v[56:57], v[136:137]
	v_pk_mul_f32 v[46:47], v[58:59], v[138:139]
	ds_write2_b64 v68, v[42:43], v[0:1] offset0:168 offset1:172
	v_pk_mul_f32 v[0:1], v[24:25], v[140:141]
	v_pk_mul_f32 v[2:3], v[26:27], v[142:143]
	v_cvt_pk_bf16_f32 v98, v108, v109
	v_cvt_pk_bf16_f32 v108, v120, v121
	v_cvt_pk_bf16_f32 v109, v122, v123
	v_cvt_pk_bf16_f32 v64, v64, v65
	v_cvt_pk_bf16_f32 v65, v66, v67
	v_add_u32_e32 v69, 0x6000, v144
	v_cvt_pk_bf16_f32 v44, v44, v45
	v_cvt_pk_bf16_f32 v45, v46, v47
	v_cvt_pk_bf16_f32 v0, v0, v1
	v_cvt_pk_bf16_f32 v1, v2, v3
	v_pk_mul_f32 v[104:105], v[104:105], v[128:129]
	v_pk_mul_f32 v[110:111], v[110:111], v[130:131]
	v_pk_mul_f32 v[112:113], v[112:113], v[128:129]
	v_pk_mul_f32 v[114:115], v[114:115], v[130:131]
	v_pk_mul_f32 v[124:125], v[124:125], v[128:129]
	v_pk_mul_f32 v[126:127], v[126:127], v[130:131]
	v_pk_mul_f32 v[84:85], v[84:85], v[132:133]
	v_pk_mul_f32 v[86:87], v[86:87], v[134:135]
	v_pk_mul_f32 v[92:93], v[92:93], v[132:133]
	v_pk_mul_f32 v[94:95], v[94:95], v[134:135]
	v_pk_mul_f32 v[100:101], v[100:101], v[132:133]
	v_pk_mul_f32 v[102:103], v[102:103], v[134:135]
	ds_write2_b64 v69, v[108:109], v[64:65] offset0:192 offset1:196
	v_pk_mul_f32 v[64:65], v[72:73], v[132:133]
	v_pk_mul_f32 v[66:67], v[74:75], v[134:135]
	v_pk_mul_f32 v[46:47], v[60:61], v[136:137]
	v_pk_mul_f32 v[48:49], v[62:63], v[138:139]
	ds_write2_b64 v69, v[44:45], v[0:1] offset0:200 offset1:204
	v_pk_mul_f32 v[0:1], v[28:29], v[140:141]
	v_pk_mul_f32 v[2:3], v[30:31], v[142:143]
	v_cvt_pk_bf16_f32 v96, v104, v105
	v_cvt_pk_bf16_f32 v99, v110, v111
	v_cvt_pk_bf16_f32 v104, v112, v113
	v_cvt_pk_bf16_f32 v105, v114, v115
	v_cvt_pk_bf16_f32 v110, v124, v125
	v_cvt_pk_bf16_f32 v111, v126, v127
	v_cvt_pk_bf16_f32 v76, v84, v85
	v_cvt_pk_bf16_f32 v77, v86, v87
	v_cvt_pk_bf16_f32 v78, v92, v93
	v_cvt_pk_bf16_f32 v79, v94, v95
	v_cvt_pk_bf16_f32 v84, v100, v101
	v_cvt_pk_bf16_f32 v85, v102, v103
	v_cvt_pk_bf16_f32 v64, v64, v65
	v_cvt_pk_bf16_f32 v65, v66, v67
	v_add_u32_e32 v66, 0x7000, v144
	v_cvt_pk_bf16_f32 v46, v46, v47
	v_cvt_pk_bf16_f32 v47, v48, v49
	v_cvt_pk_bf16_f32 v0, v0, v1
	v_cvt_pk_bf16_f32 v1, v2, v3
	v_mov_b32_e32 v2, v218
	ds_write2_b64 v146, v[96:97], v[76:77] offset0:64 offset1:68
	ds_write2_b64 v147, v[98:99], v[78:79] offset0:96 offset1:100
	ds_write2_b64 v148, v[104:105], v[84:85] offset0:128 offset1:132
	ds_write2_b64 v66, v[110:111], v[64:65] offset0:224 offset1:228
	ds_write2_b64 v66, v[46:47], v[0:1] offset0:232 offset1:236
	s_waitcnt lgkmcnt(0)
	s_barrier
; DI int tidx() { int t = __builtin_amdgcn_workitem_id_x(); asm volatile("" : "+v"(t)); return t; }
; DI unsigned cvtpk(float lo, float hi) { const f32x2_ v = {lo, hi}; return __builtin_bit_cast(unsigned, __builtin_convertvector(v, bf16x2_)); }
; DI float bflo(unsigned w) { return __uint_as_float(w << 16); }
; DI float bfhi(unsigned w) { return __uint_as_float(w & 0xffff0000u); }
; DI void phase6(const Params& p, const Sched& sched, unsigned char* smem) {
;     ...
;       const int tid = tidx();
; #pragma unroll
;       for (int i = 0; i < 16; ++i) {
;         const int c = tid + 256 * i, row = c >> 4, ch = (c & 15) * 8;
;         const size_t gi = (size_t)(tm * 256 + row) * 1024 + tn * 128 + ch;
;         const u32x4 sv = *(const u32x4*)(Ls + row * EST + ch);
;         const f32x4 x0 = *(const f32x4*)(p.x + gi), x1 = *(const f32x4*)(p.x + gi + 4);
;         u32x4 w;
;         w.x = cvtpk(x0[0] + bflo(sv.x), x0[1] + bfhi(sv.x)); w.y = cvtpk(x0[2] + bflo(sv.y), x0[3] + bfhi(sv.y));
;         w.z = cvtpk(x1[0] + bflo(sv.z), x1[1] + bfhi(sv.z)); w.w = cvtpk(x1[2] + bflo(sv.w), x1[3] + bfhi(sv.w));
;         *(u32x4*)(x1b + gi) = w;
;       }
	s_nop 0
	v_ashrrev_i32_e32 v3, 4, v2
	v_add_u32_e32 v4, s33, v3
	v_lshlrev_b32_e32 v0, 3, v2
	v_ashrrev_i32_e32 v5, 31, v4
	v_and_b32_e32 v1, 0x78, v0
	v_lshlrev_b64 v[16:17], 10, v[4:5]
	v_or3_b32 v16, v16, s34, v1
	v_lshl_add_u64 v[8:9], v[16:17], 2, s[76:77]
	global_load_dwordx4 v[4:7], v[8:9], off
	v_lshlrev_b32_e32 v0, 1, v1
	global_load_dwordx4 v[8:11], v[8:9], off offset:16
	v_mad_u64_u32 v[12:13], s[36:37], v3, s27, v[0:1]
	ds_read_b128 v[12:15], v12
	v_add_u32_e32 v3, 0x100, v2
	v_ashrrev_i32_e32 v3, 4, v3
	s_waitcnt lgkmcnt(0)
	v_lshlrev_b32_e32 v18, 16, v12
	v_and_b32_e32 v19, 0xffff0000, v12
	v_lshlrev_b32_e32 v12, 16, v13
	v_and_b32_e32 v13, 0xffff0000, v13
	s_waitcnt vmcnt(1)
	v_pk_add_f32 v[4:5], v[4:5], v[18:19]
	v_pk_add_f32 v[6:7], v[6:7], v[12:13]
	v_cvt_pk_bf16_f32 v4, v4, v5
	v_cvt_pk_bf16_f32 v5, v6, v7
	v_lshlrev_b32_e32 v6, 16, v14
	v_and_b32_e32 v7, 0xffff0000, v14
	s_waitcnt vmcnt(0)
	v_pk_add_f32 v[6:7], v[8:9], v[6:7]
	v_lshlrev_b32_e32 v8, 16, v15
	v_and_b32_e32 v9, 0xffff0000, v15
	v_pk_add_f32 v[8:9], v[10:11], v[8:9]
	v_cvt_pk_bf16_f32 v6, v6, v7
	v_cvt_pk_bf16_f32 v7, v8, v9
	v_lshl_add_u64 v[8:9], v[16:17], 1, s[12:13]
	global_store_dwordx4 v[8:9], v[4:7], off
	v_add_u32_e32 v12, 0x200, v2
	v_ashrrev_i32_e32 v26, 4, v12
	v_add_u32_e32 v4, s33, v3
	v_ashrrev_i32_e32 v5, 31, v4
	v_lshlrev_b64 v[16:17], 10, v[4:5]
	v_or3_b32 v16, v16, s34, v1
	v_lshl_add_u64 v[8:9], v[16:17], 2, s[76:77]
	global_load_dwordx4 v[4:7], v[8:9], off
	v_mad_u64_u32 v[12:13], s[36:37], v3, s27, v[0:1]
	global_load_dwordx4 v[8:11], v[8:9], off offset:16
	ds_read_b128 v[12:15], v12
	v_add_u32_e32 v18, s33, v26
	v_ashrrev_i32_e32 v19, 31, v18
	v_lshlrev_b64 v[18:19], 10, v[18:19]
	v_or3_b32 v18, v18, s34, v1
	s_waitcnt lgkmcnt(0)
	v_lshlrev_b32_e32 v22, 16, v12
	v_and_b32_e32 v23, 0xffff0000, v12
	v_lshlrev_b32_e32 v12, 16, v13
	v_and_b32_e32 v13, 0xffff0000, v13
	v_lshlrev_b32_e32 v24, 16, v14
	v_and_b32_e32 v25, 0xffff0000, v14
	v_lshlrev_b32_e32 v14, 16, v15
	v_and_b32_e32 v15, 0xffff0000, v15
	v_lshl_add_u64 v[16:17], v[16:17], 1, s[12:13]
	v_lshl_add_u64 v[20:21], v[18:19], 2, s[76:77]
	v_add_u32_e32 v3, 0x300, v2
	v_ashrrev_i32_e32 v3, 4, v3
	v_lshl_add_u64 v[18:19], v[18:19], 1, s[12:13]
	s_waitcnt vmcnt(1)
	v_pk_add_f32 v[4:5], v[4:5], v[22:23]
	v_pk_add_f32 v[6:7], v[6:7], v[12:13]
	v_cvt_pk_bf16_f32 v4, v4, v5
	s_waitcnt vmcnt(0)
	v_pk_add_f32 v[8:9], v[8:9], v[24:25]
	v_pk_add_f32 v[10:11], v[10:11], v[14:15]
	v_cvt_pk_bf16_f32 v5, v6, v7
	v_cvt_pk_bf16_f32 v6, v8, v9
	v_cvt_pk_bf16_f32 v7, v10, v11
	global_store_dwordx4 v[16:17], v[4:7], off
	global_load_dwordx4 v[4:7], v[20:21], off
	v_mad_u64_u32 v[12:13], s[36:37], v26, s27, v[0:1]
	global_load_dwordx4 v[8:11], v[20:21], off offset:16
	ds_read_b128 v[12:15], v12
	v_add_u32_e32 v16, s33, v3
	v_ashrrev_i32_e32 v17, 31, v16
	v_lshlrev_b64 v[16:17], 10, v[16:17]
	v_or3_b32 v16, v16, s34, v1
	s_waitcnt lgkmcnt(0)
	v_lshlrev_b32_e32 v22, 16, v12
	v_and_b32_e32 v23, 0xffff0000, v12
	v_lshlrev_b32_e32 v12, 16, v13
	v_and_b32_e32 v13, 0xffff0000, v13
	v_lshlrev_b32_e32 v24, 16, v14
	v_and_b32_e32 v25, 0xffff0000, v14
	v_lshlrev_b32_e32 v14, 16, v15
	v_and_b32_e32 v15, 0xffff0000, v15
	v_lshl_add_u64 v[20:21], v[16:17], 2, s[76:77]
	v_lshl_add_u64 v[16:17], v[16:17], 1, s[12:13]
	s_waitcnt vmcnt(1)
	v_pk_add_f32 v[4:5], v[4:5], v[22:23]
	v_pk_add_f32 v[6:7], v[6:7], v[12:13]
	v_cvt_pk_bf16_f32 v4, v4, v5
	s_waitcnt vmcnt(0)
	v_pk_add_f32 v[8:9], v[8:9], v[24:25]
	v_pk_add_f32 v[10:11], v[10:11], v[14:15]
	v_cvt_pk_bf16_f32 v5, v6, v7
	v_cvt_pk_bf16_f32 v6, v8, v9
	v_cvt_pk_bf16_f32 v7, v10, v11
	global_store_dwordx4 v[18:19], v[4:7], off
	global_load_dwordx4 v[4:7], v[20:21], off
	v_add_u32_e32 v12, 0x400, v2
	global_load_dwordx4 v[8:11], v[20:21], off offset:16
	v_ashrrev_i32_e32 v26, 4, v12
	v_mad_u64_u32 v[12:13], s[36:37], v3, s27, v[0:1]
	ds_read_b128 v[12:15], v12
	v_add_u32_e32 v18, s33, v26
	v_ashrrev_i32_e32 v19, 31, v18
	v_lshlrev_b64 v[18:19], 10, v[18:19]
	v_or3_b32 v18, v18, s34, v1
	s_waitcnt lgkmcnt(0)
	v_lshlrev_b32_e32 v22, 16, v12
	v_and_b32_e32 v23, 0xffff0000, v12
	v_lshlrev_b32_e32 v12, 16, v13
	v_and_b32_e32 v13, 0xffff0000, v13
	v_lshlrev_b32_e32 v24, 16, v14
	v_and_b32_e32 v25, 0xffff0000, v14
	v_lshlrev_b32_e32 v14, 16, v15
	v_and_b32_e32 v15, 0xffff0000, v15
	v_lshl_add_u64 v[20:21], v[18:19], 2, s[76:77]
	v_add_u32_e32 v3, 0x500, v2
	v_ashrrev_i32_e32 v3, 4, v3
	v_lshl_add_u64 v[18:19], v[18:19], 1, s[12:13]
	s_waitcnt vmcnt(1)
	v_pk_add_f32 v[4:5], v[4:5], v[22:23]
	v_pk_add_f32 v[6:7], v[6:7], v[12:13]
	s_waitcnt vmcnt(0)
	v_pk_add_f32 v[8:9], v[8:9], v[24:25]
	v_pk_add_f32 v[10:11], v[10:11], v[14:15]
	v_cvt_pk_bf16_f32 v4, v4, v5
	v_cvt_pk_bf16_f32 v5, v6, v7
	v_cvt_pk_bf16_f32 v6, v8, v9
	v_cvt_pk_bf16_f32 v7, v10, v11
	global_store_dwordx4 v[16:17], v[4:7], off
	global_load_dwordx4 v[4:7], v[20:21], off
	v_mad_u64_u32 v[12:13], s[36:37], v26, s27, v[0:1]
	global_load_dwordx4 v[8:11], v[20:21], off offset:16
	ds_read_b128 v[12:15], v12
	v_add_u32_e32 v16, s33, v3
	v_ashrrev_i32_e32 v17, 31, v16
	v_lshlrev_b64 v[16:17], 10, v[16:17]
	v_or3_b32 v16, v16, s34, v1
	s_waitcnt lgkmcnt(0)
	v_lshlrev_b32_e32 v22, 16, v12
	v_and_b32_e32 v23, 0xffff0000, v12
	v_lshlrev_b32_e32 v12, 16, v13
	v_and_b32_e32 v13, 0xffff0000, v13
	v_lshlrev_b32_e32 v24, 16, v14
	v_and_b32_e32 v25, 0xffff0000, v14
	v_lshlrev_b32_e32 v14, 16, v15
	v_and_b32_e32 v15, 0xffff0000, v15
	v_lshl_add_u64 v[20:21], v[16:17], 2, s[76:77]
	v_lshl_add_u64 v[16:17], v[16:17], 1, s[12:13]
	s_waitcnt vmcnt(1)
	v_pk_add_f32 v[4:5], v[4:5], v[22:23]
	v_pk_add_f32 v[6:7], v[6:7], v[12:13]
	v_cvt_pk_bf16_f32 v4, v4, v5
	s_waitcnt vmcnt(0)
; DI int tidx() { int t = __builtin_amdgcn_workitem_id_x(); asm volatile("" : "+v"(t)); return t; }
; DI unsigned cvtpk(float lo, float hi) { const f32x2_ v = {lo, hi}; return __builtin_bit_cast(unsigned, __builtin_convertvector(v, bf16x2_)); }
; DI float bflo(unsigned w) { return __uint_as_float(w << 16); }
; DI float bfhi(unsigned w) { return __uint_as_float(w & 0xffff0000u); }
; DI void phase6(const Params& p, const Sched& sched, unsigned char* smem) {
;     ...
;       const int tid = tidx();
; #pragma unroll
;       for (int i = 0; i < 16; ++i) {
;         const int c = tid + 256 * i, row = c >> 4, ch = (c & 15) * 8;
;         const size_t gi = (size_t)(tm * 256 + row) * 1024 + tn * 128 + ch;
;         const u32x4 sv = *(const u32x4*)(Ls + row * EST + ch);
;         const f32x4 x0 = *(const f32x4*)(p.x + gi), x1 = *(const f32x4*)(p.x + gi + 4);
;         u32x4 w;
;         w.x = cvtpk(x0[0] + bflo(sv.x), x0[1] + bfhi(sv.x)); w.y = cvtpk(x0[2] + bflo(sv.y), x0[3] + bfhi(sv.y));
;         w.z = cvtpk(x1[0] + bflo(sv.z), x1[1] + bfhi(sv.z)); w.w = cvtpk(x1[2] + bflo(sv.w), x1[3] + bfhi(sv.w));
;         *(u32x4*)(x1b + gi) = w;
;       }
	v_pk_add_f32 v[8:9], v[8:9], v[24:25]
	v_pk_add_f32 v[10:11], v[10:11], v[14:15]
	v_cvt_pk_bf16_f32 v5, v6, v7
	v_cvt_pk_bf16_f32 v6, v8, v9
	v_cvt_pk_bf16_f32 v7, v10, v11
	global_store_dwordx4 v[18:19], v[4:7], off
	global_load_dwordx4 v[4:7], v[20:21], off
	v_add_u32_e32 v12, 0x600, v2
	global_load_dwordx4 v[8:11], v[20:21], off offset:16
	v_ashrrev_i32_e32 v26, 4, v12
	v_mad_u64_u32 v[12:13], s[36:37], v3, s27, v[0:1]
	ds_read_b128 v[12:15], v12
	v_add_u32_e32 v18, s33, v26
	v_ashrrev_i32_e32 v19, 31, v18
	v_lshlrev_b64 v[18:19], 10, v[18:19]
	v_or3_b32 v18, v18, s34, v1
	s_waitcnt lgkmcnt(0)
	v_lshlrev_b32_e32 v22, 16, v12
	v_and_b32_e32 v23, 0xffff0000, v12
	v_lshlrev_b32_e32 v12, 16, v13
	v_and_b32_e32 v13, 0xffff0000, v13
	v_lshlrev_b32_e32 v24, 16, v14
	v_and_b32_e32 v25, 0xffff0000, v14
	v_lshlrev_b32_e32 v14, 16, v15
	v_and_b32_e32 v15, 0xffff0000, v15
	v_lshl_add_u64 v[20:21], v[18:19], 2, s[76:77]
	v_add_u32_e32 v3, 0x700, v2
	v_ashrrev_i32_e32 v3, 4, v3
	v_lshl_add_u64 v[18:19], v[18:19], 1, s[12:13]
	s_waitcnt vmcnt(1)
	v_pk_add_f32 v[4:5], v[4:5], v[22:23]
	v_pk_add_f32 v[6:7], v[6:7], v[12:13]
	s_waitcnt vmcnt(0)
	v_pk_add_f32 v[8:9], v[8:9], v[24:25]
	v_pk_add_f32 v[10:11], v[10:11], v[14:15]
	v_cvt_pk_bf16_f32 v4, v4, v5
	v_cvt_pk_bf16_f32 v5, v6, v7
	v_cvt_pk_bf16_f32 v6, v8, v9
	v_cvt_pk_bf16_f32 v7, v10, v11
	global_store_dwordx4 v[16:17], v[4:7], off
	global_load_dwordx4 v[4:7], v[20:21], off
	v_mad_u64_u32 v[12:13], s[36:37], v26, s27, v[0:1]
	global_load_dwordx4 v[8:11], v[20:21], off offset:16
	ds_read_b128 v[12:15], v12
	v_add_u32_e32 v16, s33, v3
	v_ashrrev_i32_e32 v17, 31, v16
	v_lshlrev_b64 v[16:17], 10, v[16:17]
	v_or3_b32 v16, v16, s34, v1
	s_waitcnt lgkmcnt(0)
	v_lshlrev_b32_e32 v22, 16, v12
	v_and_b32_e32 v23, 0xffff0000, v12
	v_lshlrev_b32_e32 v12, 16, v13
	v_and_b32_e32 v13, 0xffff0000, v13
	v_lshlrev_b32_e32 v24, 16, v14
	v_and_b32_e32 v25, 0xffff0000, v14
	v_lshlrev_b32_e32 v14, 16, v15
	v_and_b32_e32 v15, 0xffff0000, v15
	v_lshl_add_u64 v[20:21], v[16:17], 2, s[76:77]
	v_lshl_add_u64 v[16:17], v[16:17], 1, s[12:13]
	s_waitcnt vmcnt(1)
	v_pk_add_f32 v[4:5], v[4:5], v[22:23]
	v_pk_add_f32 v[6:7], v[6:7], v[12:13]
	v_cvt_pk_bf16_f32 v4, v4, v5
	s_waitcnt vmcnt(0)
	v_pk_add_f32 v[8:9], v[8:9], v[24:25]
	v_pk_add_f32 v[10:11], v[10:11], v[14:15]
	v_cvt_pk_bf16_f32 v5, v6, v7
	v_cvt_pk_bf16_f32 v6, v8, v9
	v_cvt_pk_bf16_f32 v7, v10, v11
	global_store_dwordx4 v[18:19], v[4:7], off
	global_load_dwordx4 v[4:7], v[20:21], off
	v_add_u32_e32 v12, 0x800, v2
	global_load_dwordx4 v[8:11], v[20:21], off offset:16
	v_ashrrev_i32_e32 v26, 4, v12
	v_mad_u64_u32 v[12:13], s[36:37], v3, s27, v[0:1]
	ds_read_b128 v[12:15], v12
	v_add_u32_e32 v18, s33, v26
	v_ashrrev_i32_e32 v19, 31, v18
	v_lshlrev_b64 v[18:19], 10, v[18:19]
	v_or3_b32 v18, v18, s34, v1
	s_waitcnt lgkmcnt(0)
	v_lshlrev_b32_e32 v22, 16, v12
	v_and_b32_e32 v23, 0xffff0000, v12
	v_lshlrev_b32_e32 v12, 16, v13
	v_and_b32_e32 v13, 0xffff0000, v13
	v_lshlrev_b32_e32 v24, 16, v14
	v_and_b32_e32 v25, 0xffff0000, v14
	v_lshlrev_b32_e32 v14, 16, v15
	v_and_b32_e32 v15, 0xffff0000, v15
	v_lshl_add_u64 v[20:21], v[18:19], 2, s[76:77]
	v_add_u32_e32 v3, 0x900, v2
	v_ashrrev_i32_e32 v3, 4, v3
	v_lshl_add_u64 v[18:19], v[18:19], 1, s[12:13]
	s_waitcnt vmcnt(1)
	v_pk_add_f32 v[4:5], v[4:5], v[22:23]
	v_pk_add_f32 v[6:7], v[6:7], v[12:13]
	s_waitcnt vmcnt(0)
	v_pk_add_f32 v[8:9], v[8:9], v[24:25]
	v_pk_add_f32 v[10:11], v[10:11], v[14:15]
	v_cvt_pk_bf16_f32 v4, v4, v5
	v_cvt_pk_bf16_f32 v5, v6, v7
	v_cvt_pk_bf16_f32 v6, v8, v9
	v_cvt_pk_bf16_f32 v7, v10, v11
	global_store_dwordx4 v[16:17], v[4:7], off
	global_load_dwordx4 v[4:7], v[20:21], off
	v_mad_u64_u32 v[12:13], s[36:37], v26, s27, v[0:1]
	global_load_dwordx4 v[8:11], v[20:21], off offset:16
	ds_read_b128 v[12:15], v12
	v_add_u32_e32 v16, s33, v3
	v_ashrrev_i32_e32 v17, 31, v16
	v_lshlrev_b64 v[16:17], 10, v[16:17]
	v_or3_b32 v16, v16, s34, v1
	s_waitcnt lgkmcnt(0)
	v_lshlrev_b32_e32 v22, 16, v12
	v_and_b32_e32 v23, 0xffff0000, v12
	v_lshlrev_b32_e32 v12, 16, v13
	v_and_b32_e32 v13, 0xffff0000, v13
	v_lshlrev_b32_e32 v24, 16, v14
	v_and_b32_e32 v25, 0xffff0000, v14
	v_lshlrev_b32_e32 v14, 16, v15
	v_and_b32_e32 v15, 0xffff0000, v15
	v_lshl_add_u64 v[20:21], v[16:17], 2, s[76:77]
	v_lshl_add_u64 v[16:17], v[16:17], 1, s[12:13]
	s_waitcnt vmcnt(1)
	v_pk_add_f32 v[4:5], v[4:5], v[22:23]
	v_pk_add_f32 v[6:7], v[6:7], v[12:13]
	v_cvt_pk_bf16_f32 v4, v4, v5
	s_waitcnt vmcnt(0)
	v_pk_add_f32 v[8:9], v[8:9], v[24:25]
	v_pk_add_f32 v[10:11], v[10:11], v[14:15]
	v_cvt_pk_bf16_f32 v5, v6, v7
	v_cvt_pk_bf16_f32 v6, v8, v9
	v_cvt_pk_bf16_f32 v7, v10, v11
	global_store_dwordx4 v[18:19], v[4:7], off
	global_load_dwordx4 v[4:7], v[20:21], off
	v_add_u32_e32 v12, 0xa00, v2
	global_load_dwordx4 v[8:11], v[20:21], off offset:16
	v_ashrrev_i32_e32 v26, 4, v12
	v_mad_u64_u32 v[12:13], s[36:37], v3, s27, v[0:1]
	ds_read_b128 v[12:15], v12
	v_add_u32_e32 v18, s33, v26
	v_ashrrev_i32_e32 v19, 31, v18
	v_lshlrev_b64 v[18:19], 10, v[18:19]
	v_or3_b32 v18, v18, s34, v1
	s_waitcnt lgkmcnt(0)
	v_lshlrev_b32_e32 v22, 16, v12
	v_and_b32_e32 v23, 0xffff0000, v12
	v_lshlrev_b32_e32 v12, 16, v13
	v_and_b32_e32 v13, 0xffff0000, v13
	v_lshlrev_b32_e32 v24, 16, v14
	v_and_b32_e32 v25, 0xffff0000, v14
	v_lshlrev_b32_e32 v14, 16, v15
	v_and_b32_e32 v15, 0xffff0000, v15
	v_lshl_add_u64 v[20:21], v[18:19], 2, s[76:77]
	v_add_u32_e32 v3, 0xb00, v2
	v_ashrrev_i32_e32 v3, 4, v3
	v_lshl_add_u64 v[18:19], v[18:19], 1, s[12:13]
	s_waitcnt vmcnt(1)
	v_pk_add_f32 v[4:5], v[4:5], v[22:23]
	v_pk_add_f32 v[6:7], v[6:7], v[12:13]
	s_waitcnt vmcnt(0)
; DI int tidx() { int t = __builtin_amdgcn_workitem_id_x(); asm volatile("" : "+v"(t)); return t; }
; DI unsigned cvtpk(float lo, float hi) { const f32x2_ v = {lo, hi}; return __builtin_bit_cast(unsigned, __builtin_convertvector(v, bf16x2_)); }
; DI float bflo(unsigned w) { return __uint_as_float(w << 16); }
; DI float bfhi(unsigned w) { return __uint_as_float(w & 0xffff0000u); }
; template <class F> DI void for_tiles_st(int ntm, int ntn, const Sched& sc, F f) {
;     ...
;     for (int sp = sc.xd; sp < nsuper; sp += sc.nx) {
;       const int sm = sp / nsn, sn = sp - sm * nsn;
;       for (int qq = sc.rank; qq < 64; qq += sc.nloc) f(sm * 8 + (qq >> 3), sn * 8 + (qq & 7));
; DI void phase6(const Params& p, const Sched& sched, unsigned char* smem) {
;     ...
;       const int tid = tidx();
; #pragma unroll
;       for (int i = 0; i < 16; ++i) {
;         const int c = tid + 256 * i, row = c >> 4, ch = (c & 15) * 8;
;         const size_t gi = (size_t)(tm * 256 + row) * 1024 + tn * 128 + ch;
;         const u32x4 sv = *(const u32x4*)(Ls + row * EST + ch);
;         const f32x4 x0 = *(const f32x4*)(p.x + gi), x1 = *(const f32x4*)(p.x + gi + 4);
;         u32x4 w;
;         w.x = cvtpk(x0[0] + bflo(sv.x), x0[1] + bfhi(sv.x)); w.y = cvtpk(x0[2] + bflo(sv.y), x0[3] + bfhi(sv.y));
;         w.z = cvtpk(x1[0] + bflo(sv.z), x1[1] + bfhi(sv.z)); w.w = cvtpk(x1[2] + bflo(sv.w), x1[3] + bfhi(sv.w));
;         *(u32x4*)(x1b + gi) = w;
;       }
	v_pk_add_f32 v[8:9], v[8:9], v[24:25]
	v_pk_add_f32 v[10:11], v[10:11], v[14:15]
	v_cvt_pk_bf16_f32 v4, v4, v5
	v_cvt_pk_bf16_f32 v5, v6, v7
	v_cvt_pk_bf16_f32 v6, v8, v9
	v_cvt_pk_bf16_f32 v7, v10, v11
	global_store_dwordx4 v[16:17], v[4:7], off
	global_load_dwordx4 v[4:7], v[20:21], off
	v_mad_u64_u32 v[12:13], s[36:37], v26, s27, v[0:1]
	global_load_dwordx4 v[8:11], v[20:21], off offset:16
	ds_read_b128 v[12:15], v12
	v_add_u32_e32 v16, s33, v3
	v_ashrrev_i32_e32 v17, 31, v16
	v_lshlrev_b64 v[16:17], 10, v[16:17]
	v_or3_b32 v16, v16, s34, v1
	s_waitcnt lgkmcnt(0)
	v_lshlrev_b32_e32 v22, 16, v12
	v_and_b32_e32 v23, 0xffff0000, v12
	v_lshlrev_b32_e32 v12, 16, v13
	v_and_b32_e32 v13, 0xffff0000, v13
	v_lshlrev_b32_e32 v24, 16, v14
	v_and_b32_e32 v25, 0xffff0000, v14
	v_lshlrev_b32_e32 v14, 16, v15
	v_and_b32_e32 v15, 0xffff0000, v15
	v_lshl_add_u64 v[20:21], v[16:17], 2, s[76:77]
	v_lshl_add_u64 v[16:17], v[16:17], 1, s[12:13]
	s_waitcnt vmcnt(1)
	v_pk_add_f32 v[4:5], v[4:5], v[22:23]
	v_pk_add_f32 v[6:7], v[6:7], v[12:13]
	v_cvt_pk_bf16_f32 v4, v4, v5
	s_waitcnt vmcnt(0)
	v_pk_add_f32 v[8:9], v[8:9], v[24:25]
	v_pk_add_f32 v[10:11], v[10:11], v[14:15]
	v_cvt_pk_bf16_f32 v5, v6, v7
	v_cvt_pk_bf16_f32 v6, v8, v9
	v_cvt_pk_bf16_f32 v7, v10, v11
	global_store_dwordx4 v[18:19], v[4:7], off
	global_load_dwordx4 v[4:7], v[20:21], off
	v_add_u32_e32 v12, 0xc00, v2
	global_load_dwordx4 v[8:11], v[20:21], off offset:16
	v_ashrrev_i32_e32 v26, 4, v12
	v_mad_u64_u32 v[12:13], s[36:37], v3, s27, v[0:1]
	ds_read_b128 v[12:15], v12
	v_add_u32_e32 v18, s33, v26
	v_ashrrev_i32_e32 v19, 31, v18
	v_lshlrev_b64 v[18:19], 10, v[18:19]
	v_or3_b32 v18, v18, s34, v1
	s_waitcnt lgkmcnt(0)
	v_lshlrev_b32_e32 v22, 16, v12
	v_and_b32_e32 v23, 0xffff0000, v12
	v_lshlrev_b32_e32 v12, 16, v13
	v_and_b32_e32 v13, 0xffff0000, v13
	v_lshlrev_b32_e32 v24, 16, v14
	v_and_b32_e32 v25, 0xffff0000, v14
	v_lshlrev_b32_e32 v14, 16, v15
	v_and_b32_e32 v15, 0xffff0000, v15
	v_lshl_add_u64 v[20:21], v[18:19], 2, s[76:77]
	v_add_u32_e32 v3, 0xd00, v2
	v_ashrrev_i32_e32 v3, 4, v3
	v_lshl_add_u64 v[18:19], v[18:19], 1, s[12:13]
	s_waitcnt vmcnt(1)
	v_pk_add_f32 v[4:5], v[4:5], v[22:23]
	v_pk_add_f32 v[6:7], v[6:7], v[12:13]
	s_waitcnt vmcnt(0)
	v_pk_add_f32 v[8:9], v[8:9], v[24:25]
	v_pk_add_f32 v[10:11], v[10:11], v[14:15]
	v_cvt_pk_bf16_f32 v4, v4, v5
	v_cvt_pk_bf16_f32 v5, v6, v7
	v_cvt_pk_bf16_f32 v6, v8, v9
	v_cvt_pk_bf16_f32 v7, v10, v11
	global_store_dwordx4 v[16:17], v[4:7], off
	global_load_dwordx4 v[4:7], v[20:21], off
	v_mad_u64_u32 v[12:13], s[36:37], v26, s27, v[0:1]
	global_load_dwordx4 v[8:11], v[20:21], off offset:16
	ds_read_b128 v[12:15], v12
	v_add_u32_e32 v16, s33, v3
	v_ashrrev_i32_e32 v17, 31, v16
	v_lshlrev_b64 v[16:17], 10, v[16:17]
	v_or3_b32 v16, v16, s34, v1
	s_waitcnt lgkmcnt(0)
	v_lshlrev_b32_e32 v22, 16, v12
	v_and_b32_e32 v23, 0xffff0000, v12
	v_lshlrev_b32_e32 v12, 16, v13
	v_and_b32_e32 v13, 0xffff0000, v13
	v_lshlrev_b32_e32 v24, 16, v14
	v_and_b32_e32 v25, 0xffff0000, v14
	v_lshlrev_b32_e32 v14, 16, v15
	v_and_b32_e32 v15, 0xffff0000, v15
	v_lshl_add_u64 v[20:21], v[16:17], 2, s[76:77]
	v_lshl_add_u64 v[16:17], v[16:17], 1, s[12:13]
	s_waitcnt vmcnt(1)
	v_pk_add_f32 v[4:5], v[4:5], v[22:23]
	v_pk_add_f32 v[6:7], v[6:7], v[12:13]
	v_cvt_pk_bf16_f32 v4, v4, v5
	s_waitcnt vmcnt(0)
	v_pk_add_f32 v[8:9], v[8:9], v[24:25]
	v_pk_add_f32 v[10:11], v[10:11], v[14:15]
	v_cvt_pk_bf16_f32 v5, v6, v7
	v_cvt_pk_bf16_f32 v6, v8, v9
	v_cvt_pk_bf16_f32 v7, v10, v11
	global_store_dwordx4 v[18:19], v[4:7], off
	global_load_dwordx4 v[4:7], v[20:21], off
	v_add_u32_e32 v12, 0xe00, v2
	global_load_dwordx4 v[8:11], v[20:21], off offset:16
	v_ashrrev_i32_e32 v26, 4, v12
	v_mad_u64_u32 v[12:13], s[36:37], v3, s27, v[0:1]
	ds_read_b128 v[12:15], v12
	v_add_u32_e32 v18, s33, v26
	v_ashrrev_i32_e32 v19, 31, v18
	v_lshlrev_b64 v[18:19], 10, v[18:19]
	v_or3_b32 v18, v18, s34, v1
	s_waitcnt lgkmcnt(0)
	v_lshlrev_b32_e32 v22, 16, v12
	v_and_b32_e32 v23, 0xffff0000, v12
	v_lshlrev_b32_e32 v12, 16, v13
	v_and_b32_e32 v13, 0xffff0000, v13
	v_lshlrev_b32_e32 v24, 16, v14
	v_and_b32_e32 v25, 0xffff0000, v14
	v_lshlrev_b32_e32 v14, 16, v15
	v_and_b32_e32 v15, 0xffff0000, v15
	v_lshl_add_u64 v[20:21], v[18:19], 2, s[76:77]
	v_add_u32_e32 v2, 0xf00, v2
	v_lshl_add_u64 v[18:19], v[18:19], 1, s[12:13]
	s_waitcnt vmcnt(1)
	v_pk_add_f32 v[4:5], v[4:5], v[22:23]
	v_pk_add_f32 v[6:7], v[6:7], v[12:13]
	s_waitcnt vmcnt(0)
	v_pk_add_f32 v[8:9], v[8:9], v[24:25]
	v_pk_add_f32 v[10:11], v[10:11], v[14:15]
	v_cvt_pk_bf16_f32 v4, v4, v5
	v_cvt_pk_bf16_f32 v5, v6, v7
	v_cvt_pk_bf16_f32 v6, v8, v9
	v_cvt_pk_bf16_f32 v7, v10, v11
	global_store_dwordx4 v[16:17], v[4:7], off
	global_load_dwordx4 v[4:7], v[20:21], off
	v_mad_u64_u32 v[12:13], s[36:37], v26, s27, v[0:1]
	global_load_dwordx4 v[8:11], v[20:21], off offset:16
	ds_read_b128 v[12:15], v12
	v_ashrrev_i32_e32 v24, 4, v2
	v_add_u32_e32 v2, s33, v24
	v_ashrrev_i32_e32 v3, 31, v2
	v_lshlrev_b64 v[16:17], 10, v[2:3]
	s_waitcnt lgkmcnt(0)
	v_lshlrev_b32_e32 v2, 16, v12
	v_and_b32_e32 v3, 0xffff0000, v12
	v_lshlrev_b32_e32 v12, 16, v13
	v_and_b32_e32 v13, 0xffff0000, v13
	v_lshlrev_b32_e32 v22, 16, v14
	v_and_b32_e32 v23, 0xffff0000, v14
	v_lshlrev_b32_e32 v14, 16, v15
	v_and_b32_e32 v15, 0xffff0000, v15
	v_or3_b32 v16, v16, s34, v1
	v_lshl_add_u64 v[20:21], v[16:17], 2, s[76:77]
	v_mad_u64_u32 v[0:1], s[34:35], v24, s27, v[0:1]
	s_waitcnt vmcnt(1)
	v_pk_add_f32 v[2:3], v[4:5], v[2:3]
	v_pk_add_f32 v[4:5], v[6:7], v[12:13]
	v_cvt_pk_bf16_f32 v2, v2, v3
	s_waitcnt vmcnt(0)
	v_pk_add_f32 v[6:7], v[8:9], v[22:23]
	v_pk_add_f32 v[8:9], v[10:11], v[14:15]
	v_cvt_pk_bf16_f32 v3, v4, v5
	v_cvt_pk_bf16_f32 v4, v6, v7
	v_cvt_pk_bf16_f32 v5, v8, v9
	global_store_dwordx4 v[18:19], v[2:5], off
	global_load_dwordx4 v[2:5], v[20:21], off
	ds_read_b128 v[10:13], v0
	global_load_dwordx4 v[6:9], v[20:21], off offset:16
	v_lshl_add_u64 v[14:15], v[16:17], 1, s[12:13]
	s_waitcnt lgkmcnt(0)
	v_lshlrev_b32_e32 v0, 16, v10
	v_and_b32_e32 v1, 0xffff0000, v10
	v_lshlrev_b32_e32 v10, 16, v11
	v_and_b32_e32 v11, 0xffff0000, v11
	v_lshlrev_b32_e32 v16, 16, v12
	v_and_b32_e32 v17, 0xffff0000, v12
	v_lshlrev_b32_e32 v12, 16, v13
	v_and_b32_e32 v13, 0xffff0000, v13
	s_waitcnt vmcnt(1)
	v_pk_add_f32 v[0:1], v[2:3], v[0:1]
	v_pk_add_f32 v[2:3], v[4:5], v[10:11]
	s_waitcnt vmcnt(0)
	v_pk_add_f32 v[4:5], v[6:7], v[16:17]
	v_pk_add_f32 v[6:7], v[8:9], v[12:13]
	v_cvt_pk_bf16_f32 v0, v0, v1
	v_cvt_pk_bf16_f32 v1, v2, v3
	v_cvt_pk_bf16_f32 v2, v4, v5
	v_cvt_pk_bf16_f32 v3, v6, v7
	global_store_dwordx4 v[14:15], v[0:3], off
	v_mov_b32_e32 v243, 0x12000
	v_readfirstlane_b32 s98, v218
	s_cmp_lg_u32 s98, 0
	s_cbranch_scc1 .Lp6_dyn_skip_b
	s_waitcnt vmcnt(16)
	s_mov_b64 s[100:101], exec
	s_mov_b64 exec, 1
	ds_write_b32 v243, v240
	s_waitcnt lgkmcnt(0)
	s_mov_b64 exec, s[100:101]

; template <class F> DI void for_tiles_st(int ntm, int ntn, const Sched& sc, F f) {
;     ...
;     for (int sp = sc.xd; sp < nsuper; sp += sc.nx) {
;       const int sm = sp / nsn, sn = sp - sm * nsn;
;       for (int qq = sc.rank; qq < 64; qq += sc.nloc) f(sm * 8 + (qq >> 3), sn * 8 + (qq & 7));
.Lp6_dyn_decode_n:
	s_and_b32 s31, s98, 63
	s_mov_b32 s30, s31
	s_lshr_b32 s99, s98, 6
	s_mul_i32 s99, s99, s79
	s_add_i32 s99, s99, s74
	s_cmp_gt_i32 s99, 31
	s_cbranch_scc1 .LBB0_814
	s_lshl_b32 s29, s99, 3
	s_mov_b32 s20, s29
	s_branch .LBB0_811

; template <class F> DI void for_tiles_st(int ntm, int ntn, const Sched& sc, F f) {
;   if ((ntn & 7) == 0) {
;     const int nsn = ntn >> 3, nsuper = (ntm >> 3) * nsn;
;     for (int sp = sc.xd; sp < nsuper; sp += sc.nx) {
;       const int sm = sp / nsn, sn = sp - sm * nsn;
;       for (int qq = sc.rank; qq < 64; qq += sc.nloc) f(sm * 8 + (qq >> 3), sn * 8 + (qq & 7));
; DI void phase9(const Params& p, const Sched& sched, unsigned char* smem) {
;   XBlk xl{(const u16*)(p.ws + OFF_ACT), Tn};
;   const float* mod = (const float*)(p.ws + OFF_MOD);
;   const u16* x1b = (const u16*)(p.ws + OFF_MA); u16* x2b = (u16*)(p.ws + OFF_MB);
;   for_tiles_st(256, 8, sched, [&](int tm, int tn) {
;     gemm_tile<8>((const u16*)(p.ws + OFF_WDN), 1024, tn * 128, tm * 256, FF, xl, [&](f32x4 (&acc)[4][8], int fb, int tb, int lr, int lq, int wf, int wt) {
.LBB0_1089:
	s_or_b64 exec, exec, s[0:1]
	s_andn2_b64 vcc, exec, s[14:15]
	s_waitcnt lgkmcnt(0)
	s_barrier
	s_cbranch_vccnz .LBB0_1097
	s_add_u32 s4, s42, 0x1700000
	s_addc_u32 s5, s43, 0
	s_add_u32 s6, s42, 0xbf00800
	s_addc_u32 s7, s43, 0
	s_cmp_lt_i32 s75, 64
	s_cselect_b64 s[0:1], -1, 0
	v_cndmask_b32_e64 v0, 0, 1, s[0:1]
	s_add_u32 s10, s42, 0x1710000
	s_addc_u32 s11, s43, 0
	s_lshl_b32 s18, s74, 3
	s_lshl_b32 s19, s79, 3
	v_cmp_ne_u32_e64 s[0:1], 1, v0
	s_movk_i32 s20, 0xc0
	s_movk_i32 s21, 0x80
	v_mov_b32_e32 v153, 0
	s_mov_b32 s22, 0x1720000
	s_mov_b32 s23, 0xc300000
	s_mov_b64 s[14:15], 0x400000
	s_mov_b64 s[16:17], 0x10000
	s_movk_i32 s24, 0x5000
	s_movk_i32 s25, 0x110
	s_mov_b32 s98, s75
	s_branch .Lp9_dyn_decode_n

; template <class F> DI void for_tiles_st(int ntm, int ntn, const Sched& sc, F f) {
;     ...
;     for (int sp = sc.xd; sp < nsuper; sp += sc.nx) {
;       const int sm = sp / nsn, sn = sp - sm * nsn;
;       for (int qq = sc.rank; qq < 64; qq += sc.nloc) f(sm * 8 + (qq >> 3), sn * 8 + (qq & 7));
.LBB0_1094:
	v_readfirstlane_b32 s30, v218
	s_cmp_lg_u32 s30, 0
	s_cbranch_scc1 .Lp9_dyn_skip_a
	s_mov_b64 s[100:101], exec
	s_mov_b64 exec, 1
	v_mov_b32_e32 v241, 0x3fb04700
	v_lshl_add_u32 v241, s74, 5, v241
	v_mov_b32_e32 v242, 1
	global_atomic_add v240, v241, v242, s[42:43] sc0
	s_mov_b64 exec, s[100:101]

; DI f32x4 mfma16(bf16x8 a, bf16x8 b, f32x4 c) { return __builtin_amdgcn_mfma_f32_16x16x32_bf16(a, b, c, 0, 0, 0); }
; template <int NI, class XL, class EP>
; DI void gemm_tile(const u16* __restrict__ W, int ldw, int f0, int t0, int K, XL xl, EP ep, unsigned char* smem) {
;     ...
;   for (int it = 0; it < nk; ++it) {
;     const u16* Ws = S0 + (it & 1) * BUF; const u16* Xs = Ws + 128 * LST;
;     __builtin_amdgcn_s_setprio(1);
;     bf16x8 a[4];
; #pragma unroll
;     for (int mi = 0; mi < 4; ++mi) a[mi] = *(const bf16x8*)(Ws + (wf * 64 + mi * 16 + lr) * LST + lq * 8);
; #pragma unroll
;     for (int ni = 0; ni < NI; ++ni) {
;       const bf16x8 b = *(const bf16x8*)(Xs + (wt * (NI * 16) + ni * 16 + lr) * LST + lq * 8);
; #pragma unroll
;       for (int mi = 0; mi < 4; ++mi) acc[mi][ni] = mfma16(a[mi], b, acc[mi][ni]);
;     }
;     __builtin_amdgcn_sched_group_barrier(0x100, 6, 0);
; #pragma unroll
;     for (int ni = 0; ni < NI; ++ni) { __builtin_amdgcn_sched_group_barrier(0x008, 4, 0); if (ni + 2 < NI) __builtin_amdgcn_sched_group_barrier(0x100, 1, 0); }
;     __builtin_amdgcn_s_setprio(0);
;     if (it + 1 < nk) lstore((it + 1) & 1);
;     if (it + 2 < nk) gload(it + 2);
;     __syncthreads();
.LBB0_1095:
	s_setprio 1
	ds_read_b128 v[168:171], v228 offset:0
	ds_read_b128 v[172:175], v228 offset:1536
	ds_read_b128 v[180:183], v228 offset:3072
	ds_read_b128 v[184:187], v228 offset:4608
	ds_read_b128 v[176:179], v152 offset:12288
	ds_read_b128 v[188:191], v152 offset:13824
	s_waitcnt lgkmcnt(1)
	v_mfma_f32_16x16x32_bf16 v[148:151], v[168:171], v[176:179], v[148:151]
	v_mfma_f32_16x16x32_bf16 v[136:139], v[172:175], v[176:179], v[136:139]
	v_mfma_f32_16x16x32_bf16 v[112:115], v[180:183], v[176:179], v[112:115]
	v_mfma_f32_16x16x32_bf16 v[80:83], v[184:187], v[176:179], v[80:83]
	ds_read_b128 v[176:179], v152 offset:15360
	s_waitcnt vmcnt(6)
	ds_write_b128 v229, v[20:23] offset:36864
	s_waitcnt lgkmcnt(2)
	v_mfma_f32_16x16x32_bf16 v[144:147], v[168:171], v[188:191], v[144:147]
	v_mfma_f32_16x16x32_bf16 v[128:131], v[172:175], v[188:191], v[128:131]
	v_mfma_f32_16x16x32_bf16 v[100:103], v[180:183], v[188:191], v[100:103]
	v_mfma_f32_16x16x32_bf16 v[68:71], v[184:187], v[188:191], v[68:71]
	ds_read_b128 v[188:191], v152 offset:16896
	ds_write_b128 v229, v[16:19] offset:36960
	global_load_dwordx4 v[20:23], v154, s[98:99]
	global_load_dwordx4 v[16:19], v154, s[98:99] offset:64
	s_waitcnt lgkmcnt(3)
	v_mfma_f32_16x16x32_bf16 v[140:143], v[168:171], v[176:179], v[140:143]
	v_mfma_f32_16x16x32_bf16 v[120:123], v[172:175], v[176:179], v[120:123]
	v_mfma_f32_16x16x32_bf16 v[88:91], v[180:183], v[176:179], v[88:91]
	v_mfma_f32_16x16x32_bf16 v[44:47], v[184:187], v[176:179], v[44:47]
	ds_read_b128 v[176:179], v152 offset:18432
	ds_write_b128 v230, v[36:39] offset:49152
	global_load_dwordx4 v[36:39], v156, s[100:101] offset:2048
	s_waitcnt lgkmcnt(3)
	v_mfma_f32_16x16x32_bf16 v[132:135], v[168:171], v[188:191], v[132:135]
	v_mfma_f32_16x16x32_bf16 v[108:111], v[172:175], v[188:191], v[108:111]
	v_mfma_f32_16x16x32_bf16 v[76:79], v[180:183], v[188:191], v[76:79]
	v_mfma_f32_16x16x32_bf16 v[40:43], v[184:187], v[188:191], v[40:43]
	ds_read_b128 v[188:191], v152 offset:19968
	ds_write_b128 v230, v[32:35] offset:49248
	global_load_dwordx4 v[32:35], v156, s[100:101] offset:2112
	s_waitcnt lgkmcnt(3)
	v_mfma_f32_16x16x32_bf16 v[124:127], v[168:171], v[176:179], v[124:127]
	v_mfma_f32_16x16x32_bf16 v[96:99], v[172:175], v[176:179], v[96:99]
	v_mfma_f32_16x16x32_bf16 v[64:67], v[180:183], v[176:179], v[64:67]
	v_mfma_f32_16x16x32_bf16 v[12:15], v[184:187], v[176:179], v[12:15]
	ds_read_b128 v[176:179], v152 offset:21504
	ds_write_b128 v230, v[28:31] offset:49344
	global_load_dwordx4 v[28:31], v156, s[100:101] offset:2176
	s_waitcnt lgkmcnt(3)
	v_mfma_f32_16x16x32_bf16 v[116:119], v[168:171], v[188:191], v[116:119]
	v_mfma_f32_16x16x32_bf16 v[84:87], v[172:175], v[188:191], v[84:87]
	v_mfma_f32_16x16x32_bf16 v[56:59], v[180:183], v[188:191], v[56:59]
	v_mfma_f32_16x16x32_bf16 v[8:11], v[184:187], v[188:191], v[8:11]
	ds_read_b128 v[188:191], v152 offset:23040
	ds_write_b128 v230, v[24:27] offset:49440
	global_load_dwordx4 v[24:27], v156, s[100:101] offset:2240
	s_waitcnt lgkmcnt(3)
	v_mfma_f32_16x16x32_bf16 v[104:107], v[168:171], v[176:179], v[104:107]
	v_mfma_f32_16x16x32_bf16 v[72:75], v[172:175], v[176:179], v[72:75]
	v_mfma_f32_16x16x32_bf16 v[52:55], v[180:183], v[176:179], v[52:55]
	v_mfma_f32_16x16x32_bf16 v[4:7], v[184:187], v[176:179], v[4:7]
	s_add_u32 s98, s98, s16
	s_addc_u32 s99, s99, s17
	s_add_u32 s100, s100, s14
	s_addc_u32 s101, s101, s15
	s_waitcnt lgkmcnt(1)
	v_mfma_f32_16x16x32_bf16 v[92:95], v[168:171], v[188:191], v[92:95]
	v_mfma_f32_16x16x32_bf16 v[60:63], v[172:175], v[188:191], v[60:63]
	v_mfma_f32_16x16x32_bf16 v[48:51], v[180:183], v[188:191], v[48:51]
	v_mfma_f32_16x16x32_bf16 v[0:3], v[184:187], v[188:191], v[0:3]
	s_setprio 0
	s_waitcnt lgkmcnt(0)
	s_barrier
	s_setprio 1
	ds_read_b128 v[168:171], v228 offset:36864
	ds_read_b128 v[172:175], v228 offset:38400
	ds_read_b128 v[180:183], v228 offset:39936
	ds_read_b128 v[184:187], v228 offset:41472
	ds_read_b128 v[176:179], v152 offset:49152
	ds_read_b128 v[188:191], v152 offset:50688
	s_waitcnt lgkmcnt(1)
	v_mfma_f32_16x16x32_bf16 v[148:151], v[168:171], v[176:179], v[148:151]
	v_mfma_f32_16x16x32_bf16 v[136:139], v[172:175], v[176:179], v[136:139]
	v_mfma_f32_16x16x32_bf16 v[112:115], v[180:183], v[176:179], v[112:115]
	v_mfma_f32_16x16x32_bf16 v[80:83], v[184:187], v[176:179], v[80:83]
	ds_read_b128 v[176:179], v152 offset:52224
	s_waitcnt vmcnt(6)
	ds_write_b128 v229, v[200:203] offset:0
	s_waitcnt lgkmcnt(2)
	v_mfma_f32_16x16x32_bf16 v[144:147], v[168:171], v[188:191], v[144:147]
	v_mfma_f32_16x16x32_bf16 v[128:131], v[172:175], v[188:191], v[128:131]
	v_mfma_f32_16x16x32_bf16 v[100:103], v[180:183], v[188:191], v[100:103]
	v_mfma_f32_16x16x32_bf16 v[68:71], v[184:187], v[188:191], v[68:71]
	ds_read_b128 v[188:191], v152 offset:53760
	ds_write_b128 v229, v[204:207] offset:96
	global_load_dwordx4 v[200:203], v154, s[98:99]
	global_load_dwordx4 v[204:207], v154, s[98:99] offset:64
	s_waitcnt lgkmcnt(3)
	v_mfma_f32_16x16x32_bf16 v[140:143], v[168:171], v[176:179], v[140:143]
	v_mfma_f32_16x16x32_bf16 v[120:123], v[172:175], v[176:179], v[120:123]
	v_mfma_f32_16x16x32_bf16 v[88:91], v[180:183], v[176:179], v[88:91]
	v_mfma_f32_16x16x32_bf16 v[44:47], v[184:187], v[176:179], v[44:47]
	ds_read_b128 v[176:179], v152 offset:55296
	ds_write_b128 v230, v[208:211] offset:12288
	global_load_dwordx4 v[208:211], v156, s[100:101] offset:2048
	s_waitcnt lgkmcnt(3)
; DI f32x4 mfma16(bf16x8 a, bf16x8 b, f32x4 c) { return __builtin_amdgcn_mfma_f32_16x16x32_bf16(a, b, c, 0, 0, 0); }
; template <int NI, class XL, class EP>
; DI void gemm_tile(const u16* __restrict__ W, int ldw, int f0, int t0, int K, XL xl, EP ep, unsigned char* smem) {
;     ...
;   for (int it = 0; it < nk; ++it) {
;     const u16* Ws = S0 + (it & 1) * BUF; const u16* Xs = Ws + 128 * LST;
;     __builtin_amdgcn_s_setprio(1);
;     bf16x8 a[4];
; #pragma unroll
;     for (int mi = 0; mi < 4; ++mi) a[mi] = *(const bf16x8*)(Ws + (wf * 64 + mi * 16 + lr) * LST + lq * 8);
; #pragma unroll
;     for (int ni = 0; ni < NI; ++ni) {
;       const bf16x8 b = *(const bf16x8*)(Xs + (wt * (NI * 16) + ni * 16 + lr) * LST + lq * 8);
; #pragma unroll
;       for (int mi = 0; mi < 4; ++mi) acc[mi][ni] = mfma16(a[mi], b, acc[mi][ni]);
;     }
;     __builtin_amdgcn_sched_group_barrier(0x100, 6, 0);
; #pragma unroll
;     for (int ni = 0; ni < NI; ++ni) { __builtin_amdgcn_sched_group_barrier(0x008, 4, 0); if (ni + 2 < NI) __builtin_amdgcn_sched_group_barrier(0x100, 1, 0); }
;     __builtin_amdgcn_s_setprio(0);
;     if (it + 1 < nk) lstore((it + 1) & 1);
;     if (it + 2 < nk) gload(it + 2);
;     __syncthreads();
	v_mfma_f32_16x16x32_bf16 v[132:135], v[168:171], v[188:191], v[132:135]
	v_mfma_f32_16x16x32_bf16 v[108:111], v[172:175], v[188:191], v[108:111]
	v_mfma_f32_16x16x32_bf16 v[76:79], v[180:183], v[188:191], v[76:79]
	v_mfma_f32_16x16x32_bf16 v[40:43], v[184:187], v[188:191], v[40:43]
	ds_read_b128 v[188:191], v152 offset:56832
	ds_write_b128 v230, v[212:215] offset:12384
	global_load_dwordx4 v[212:215], v156, s[100:101] offset:2112
	s_waitcnt lgkmcnt(3)
	v_mfma_f32_16x16x32_bf16 v[124:127], v[168:171], v[176:179], v[124:127]
	v_mfma_f32_16x16x32_bf16 v[96:99], v[172:175], v[176:179], v[96:99]
	v_mfma_f32_16x16x32_bf16 v[64:67], v[180:183], v[176:179], v[64:67]
	v_mfma_f32_16x16x32_bf16 v[12:15], v[184:187], v[176:179], v[12:15]
	ds_read_b128 v[176:179], v152 offset:58368
	ds_write_b128 v230, v[220:223] offset:12480
	global_load_dwordx4 v[220:223], v156, s[100:101] offset:2176
	s_waitcnt lgkmcnt(3)
	v_mfma_f32_16x16x32_bf16 v[116:119], v[168:171], v[188:191], v[116:119]
	v_mfma_f32_16x16x32_bf16 v[84:87], v[172:175], v[188:191], v[84:87]
	v_mfma_f32_16x16x32_bf16 v[56:59], v[180:183], v[188:191], v[56:59]
	v_mfma_f32_16x16x32_bf16 v[8:11], v[184:187], v[188:191], v[8:11]
	ds_read_b128 v[188:191], v152 offset:59904
	ds_write_b128 v230, v[224:227] offset:12576
	global_load_dwordx4 v[224:227], v156, s[100:101] offset:2240
	s_waitcnt lgkmcnt(3)
	v_mfma_f32_16x16x32_bf16 v[104:107], v[168:171], v[176:179], v[104:107]
	v_mfma_f32_16x16x32_bf16 v[72:75], v[172:175], v[176:179], v[72:75]
	v_mfma_f32_16x16x32_bf16 v[52:55], v[180:183], v[176:179], v[52:55]
	v_mfma_f32_16x16x32_bf16 v[4:7], v[184:187], v[176:179], v[4:7]
	s_add_u32 s98, s98, s16
	s_addc_u32 s99, s99, s17
	s_add_u32 s100, s100, s14
	s_addc_u32 s101, s101, s15
	s_add_i32 s33, s33, 2
	s_waitcnt lgkmcnt(1)
	v_mfma_f32_16x16x32_bf16 v[92:95], v[168:171], v[188:191], v[92:95]
	v_mfma_f32_16x16x32_bf16 v[60:63], v[172:175], v[188:191], v[60:63]
	v_mfma_f32_16x16x32_bf16 v[48:51], v[180:183], v[188:191], v[48:51]
	v_mfma_f32_16x16x32_bf16 v[0:3], v[184:187], v[188:191], v[0:3]
	s_setprio 0
	s_cmpk_lg_i32 s33, 85
	s_waitcnt lgkmcnt(0)
	s_barrier
	s_cbranch_scc1 .LBB0_1095
	s_setprio 1
	ds_read_b128 v[168:171], v228 offset:0
	ds_read_b128 v[172:175], v228 offset:1536
	ds_read_b128 v[180:183], v228 offset:3072
	ds_read_b128 v[184:187], v228 offset:4608
	ds_read_b128 v[176:179], v152 offset:12288
	ds_read_b128 v[188:191], v152 offset:13824
	s_waitcnt lgkmcnt(1)
	v_mfma_f32_16x16x32_bf16 v[148:151], v[168:171], v[176:179], v[148:151]
	v_mfma_f32_16x16x32_bf16 v[136:139], v[172:175], v[176:179], v[136:139]
	v_mfma_f32_16x16x32_bf16 v[112:115], v[180:183], v[176:179], v[112:115]
	v_mfma_f32_16x16x32_bf16 v[80:83], v[184:187], v[176:179], v[80:83]
	ds_read_b128 v[176:179], v152 offset:15360
	s_waitcnt vmcnt(6)
	ds_write_b128 v229, v[20:23] offset:36864
	s_waitcnt lgkmcnt(2)
	v_mfma_f32_16x16x32_bf16 v[144:147], v[168:171], v[188:191], v[144:147]
	v_mfma_f32_16x16x32_bf16 v[128:131], v[172:175], v[188:191], v[128:131]
	v_mfma_f32_16x16x32_bf16 v[100:103], v[180:183], v[188:191], v[100:103]
	v_mfma_f32_16x16x32_bf16 v[68:71], v[184:187], v[188:191], v[68:71]
	ds_read_b128 v[188:191], v152 offset:16896
	ds_write_b128 v229, v[16:19] offset:36960
	global_load_dwordx4 v[20:23], v154, s[98:99]
	global_load_dwordx4 v[16:19], v154, s[98:99] offset:64
	s_waitcnt lgkmcnt(3)
	v_mfma_f32_16x16x32_bf16 v[140:143], v[168:171], v[176:179], v[140:143]
	v_mfma_f32_16x16x32_bf16 v[120:123], v[172:175], v[176:179], v[120:123]
	v_mfma_f32_16x16x32_bf16 v[88:91], v[180:183], v[176:179], v[88:91]
	v_mfma_f32_16x16x32_bf16 v[44:47], v[184:187], v[176:179], v[44:47]
	ds_read_b128 v[176:179], v152 offset:18432
	ds_write_b128 v230, v[36:39] offset:49152
	global_load_dwordx4 v[36:39], v156, s[100:101] offset:2048
	s_waitcnt lgkmcnt(3)
	v_mfma_f32_16x16x32_bf16 v[132:135], v[168:171], v[188:191], v[132:135]
	v_mfma_f32_16x16x32_bf16 v[108:111], v[172:175], v[188:191], v[108:111]
	v_mfma_f32_16x16x32_bf16 v[76:79], v[180:183], v[188:191], v[76:79]
	v_mfma_f32_16x16x32_bf16 v[40:43], v[184:187], v[188:191], v[40:43]
	ds_read_b128 v[188:191], v152 offset:19968
	ds_write_b128 v230, v[32:35] offset:49248
	global_load_dwordx4 v[32:35], v156, s[100:101] offset:2112
	s_waitcnt lgkmcnt(3)
	v_mfma_f32_16x16x32_bf16 v[124:127], v[168:171], v[176:179], v[124:127]
	v_mfma_f32_16x16x32_bf16 v[96:99], v[172:175], v[176:179], v[96:99]
	v_mfma_f32_16x16x32_bf16 v[64:67], v[180:183], v[176:179], v[64:67]
	v_mfma_f32_16x16x32_bf16 v[12:15], v[184:187], v[176:179], v[12:15]
	ds_read_b128 v[176:179], v152 offset:21504
	ds_write_b128 v230, v[28:31] offset:49344
	global_load_dwordx4 v[28:31], v156, s[100:101] offset:2176
	s_waitcnt lgkmcnt(3)
	v_mfma_f32_16x16x32_bf16 v[116:119], v[168:171], v[188:191], v[116:119]
	v_mfma_f32_16x16x32_bf16 v[84:87], v[172:175], v[188:191], v[84:87]
	v_mfma_f32_16x16x32_bf16 v[56:59], v[180:183], v[188:191], v[56:59]
	v_mfma_f32_16x16x32_bf16 v[8:11], v[184:187], v[188:191], v[8:11]
	ds_read_b128 v[188:191], v152 offset:23040
	ds_write_b128 v230, v[24:27] offset:49440
	global_load_dwordx4 v[24:27], v156, s[100:101] offset:2240
	s_waitcnt lgkmcnt(3)
	v_mfma_f32_16x16x32_bf16 v[104:107], v[168:171], v[176:179], v[104:107]
	v_mfma_f32_16x16x32_bf16 v[72:75], v[172:175], v[176:179], v[72:75]
	v_mfma_f32_16x16x32_bf16 v[52:55], v[180:183], v[176:179], v[52:55]
	v_mfma_f32_16x16x32_bf16 v[4:7], v[184:187], v[176:179], v[4:7]
	s_add_u32 s98, s98, s16
	s_addc_u32 s99, s99, s17
	s_add_u32 s100, s100, s14
	s_addc_u32 s101, s101, s15
	s_waitcnt lgkmcnt(1)
	v_mfma_f32_16x16x32_bf16 v[92:95], v[168:171], v[188:191], v[92:95]
	v_mfma_f32_16x16x32_bf16 v[60:63], v[172:175], v[188:191], v[60:63]
	v_mfma_f32_16x16x32_bf16 v[48:51], v[180:183], v[188:191], v[48:51]
	v_mfma_f32_16x16x32_bf16 v[0:3], v[184:187], v[188:191], v[0:3]
	s_setprio 0
	s_waitcnt lgkmcnt(0)
	s_barrier
; DI f32x4 mfma16(bf16x8 a, bf16x8 b, f32x4 c) { return __builtin_amdgcn_mfma_f32_16x16x32_bf16(a, b, c, 0, 0, 0); }
; template <int NI, class XL, class EP>
; DI void gemm_tile(const u16* __restrict__ W, int ldw, int f0, int t0, int K, XL xl, EP ep, unsigned char* smem) {
;     ...
;   for (int it = 0; it < nk; ++it) {
;     const u16* Ws = S0 + (it & 1) * BUF; const u16* Xs = Ws + 128 * LST;
;     __builtin_amdgcn_s_setprio(1);
;     bf16x8 a[4];
; #pragma unroll
;     for (int mi = 0; mi < 4; ++mi) a[mi] = *(const bf16x8*)(Ws + (wf * 64 + mi * 16 + lr) * LST + lq * 8);
; #pragma unroll
;     for (int ni = 0; ni < NI; ++ni) {
;       const bf16x8 b = *(const bf16x8*)(Xs + (wt * (NI * 16) + ni * 16 + lr) * LST + lq * 8);
; #pragma unroll
;       for (int mi = 0; mi < 4; ++mi) acc[mi][ni] = mfma16(a[mi], b, acc[mi][ni]);
;     }
;     __builtin_amdgcn_sched_group_barrier(0x100, 6, 0);
; #pragma unroll
;     for (int ni = 0; ni < NI; ++ni) { __builtin_amdgcn_sched_group_barrier(0x008, 4, 0); if (ni + 2 < NI) __builtin_amdgcn_sched_group_barrier(0x100, 1, 0); }
;     __builtin_amdgcn_s_setprio(0);
;     if (it + 1 < nk) lstore((it + 1) & 1);
;     if (it + 2 < nk) gload(it + 2);
;     __syncthreads();
	s_setprio 1
	ds_read_b128 v[168:171], v228 offset:36864
	ds_read_b128 v[172:175], v228 offset:38400
	ds_read_b128 v[180:183], v228 offset:39936
	ds_read_b128 v[184:187], v228 offset:41472
	ds_read_b128 v[176:179], v152 offset:49152
	ds_read_b128 v[188:191], v152 offset:50688
	s_waitcnt lgkmcnt(1)
	v_mfma_f32_16x16x32_bf16 v[148:151], v[168:171], v[176:179], v[148:151]
	v_mfma_f32_16x16x32_bf16 v[136:139], v[172:175], v[176:179], v[136:139]
	v_mfma_f32_16x16x32_bf16 v[112:115], v[180:183], v[176:179], v[112:115]
	v_mfma_f32_16x16x32_bf16 v[80:83], v[184:187], v[176:179], v[80:83]
	ds_read_b128 v[176:179], v152 offset:52224
	s_waitcnt vmcnt(6)
	ds_write_b128 v229, v[200:203] offset:0
	s_waitcnt lgkmcnt(2)
	v_mfma_f32_16x16x32_bf16 v[144:147], v[168:171], v[188:191], v[144:147]
	v_mfma_f32_16x16x32_bf16 v[128:131], v[172:175], v[188:191], v[128:131]
	v_mfma_f32_16x16x32_bf16 v[100:103], v[180:183], v[188:191], v[100:103]
	v_mfma_f32_16x16x32_bf16 v[68:71], v[184:187], v[188:191], v[68:71]
	ds_read_b128 v[188:191], v152 offset:53760
	ds_write_b128 v229, v[204:207] offset:96
	s_waitcnt lgkmcnt(3)
	v_mfma_f32_16x16x32_bf16 v[140:143], v[168:171], v[176:179], v[140:143]
	v_mfma_f32_16x16x32_bf16 v[120:123], v[172:175], v[176:179], v[120:123]
	v_mfma_f32_16x16x32_bf16 v[88:91], v[180:183], v[176:179], v[88:91]
	v_mfma_f32_16x16x32_bf16 v[44:47], v[184:187], v[176:179], v[44:47]
	ds_read_b128 v[176:179], v152 offset:55296
	ds_write_b128 v230, v[208:211] offset:12288
	s_waitcnt lgkmcnt(3)
	v_mfma_f32_16x16x32_bf16 v[132:135], v[168:171], v[188:191], v[132:135]
	v_mfma_f32_16x16x32_bf16 v[108:111], v[172:175], v[188:191], v[108:111]
	v_mfma_f32_16x16x32_bf16 v[76:79], v[180:183], v[188:191], v[76:79]
	v_mfma_f32_16x16x32_bf16 v[40:43], v[184:187], v[188:191], v[40:43]
	ds_read_b128 v[188:191], v152 offset:56832
	ds_write_b128 v230, v[212:215] offset:12384
	s_waitcnt lgkmcnt(3)
	v_mfma_f32_16x16x32_bf16 v[124:127], v[168:171], v[176:179], v[124:127]
	v_mfma_f32_16x16x32_bf16 v[96:99], v[172:175], v[176:179], v[96:99]
	v_mfma_f32_16x16x32_bf16 v[64:67], v[180:183], v[176:179], v[64:67]
	v_mfma_f32_16x16x32_bf16 v[12:15], v[184:187], v[176:179], v[12:15]
	ds_read_b128 v[176:179], v152 offset:58368
	ds_write_b128 v230, v[220:223] offset:12480
	s_waitcnt lgkmcnt(3)
	v_mfma_f32_16x16x32_bf16 v[116:119], v[168:171], v[188:191], v[116:119]
	v_mfma_f32_16x16x32_bf16 v[84:87], v[172:175], v[188:191], v[84:87]
	v_mfma_f32_16x16x32_bf16 v[56:59], v[180:183], v[188:191], v[56:59]
	v_mfma_f32_16x16x32_bf16 v[8:11], v[184:187], v[188:191], v[8:11]
	ds_read_b128 v[188:191], v152 offset:59904
	ds_write_b128 v230, v[224:227] offset:12576
	s_waitcnt lgkmcnt(3)
	v_mfma_f32_16x16x32_bf16 v[104:107], v[168:171], v[176:179], v[104:107]
	v_mfma_f32_16x16x32_bf16 v[72:75], v[172:175], v[176:179], v[72:75]
	v_mfma_f32_16x16x32_bf16 v[52:55], v[180:183], v[176:179], v[52:55]
	v_mfma_f32_16x16x32_bf16 v[4:7], v[184:187], v[176:179], v[4:7]
	s_add_i32 s33, s33, 2
	s_waitcnt lgkmcnt(1)
	v_mfma_f32_16x16x32_bf16 v[92:95], v[168:171], v[188:191], v[92:95]
	v_mfma_f32_16x16x32_bf16 v[60:63], v[172:175], v[188:191], v[60:63]
	v_mfma_f32_16x16x32_bf16 v[48:51], v[180:183], v[188:191], v[48:51]
	v_mfma_f32_16x16x32_bf16 v[0:3], v[184:187], v[188:191], v[0:3]
	s_setprio 0
	s_waitcnt lgkmcnt(0)
	s_barrier
	s_setprio 1
	v_lshl_add_u32 v152, v167, 1, v164
	ds_read_b128 v[154:157], v152
	v_lshl_add_u32 v161, v165, 1, v164
	ds_read_b128 v[164:167], v152 offset:1536
	ds_read_b128 v[172:175], v152 offset:3072
	ds_read_b128 v[176:179], v152 offset:4608
	ds_read_b128 v[168:171], v161 offset:12288
	ds_read_b128 v[180:183], v161 offset:13824
	s_waitcnt lgkmcnt(1)
	v_mfma_f32_16x16x32_bf16 v[148:151], v[154:157], v[168:171], v[148:151]
	v_mfma_f32_16x16x32_bf16 v[136:139], v[164:167], v[168:171], v[136:139]
	v_mfma_f32_16x16x32_bf16 v[112:115], v[172:175], v[168:171], v[112:115]
	v_mfma_f32_16x16x32_bf16 v[80:83], v[176:179], v[168:171], v[80:83]
	ds_read_b128 v[168:171], v161 offset:15360
	s_waitcnt vmcnt(5)
	ds_write_b128 v162, v[20:23] offset:36864
	s_waitcnt lgkmcnt(2)
	v_mfma_f32_16x16x32_bf16 v[144:147], v[154:157], v[180:183], v[144:147]
	v_mfma_f32_16x16x32_bf16 v[128:131], v[164:167], v[180:183], v[128:131]
	v_mfma_f32_16x16x32_bf16 v[100:103], v[172:175], v[180:183], v[100:103]
	v_mfma_f32_16x16x32_bf16 v[68:71], v[176:179], v[180:183], v[68:71]
	ds_read_b128 v[180:183], v161 offset:16896
	s_waitcnt vmcnt(4)
	ds_write_b128 v162, v[16:19] offset:36960
	s_waitcnt lgkmcnt(3)
	v_mfma_f32_16x16x32_bf16 v[140:143], v[154:157], v[168:171], v[140:143]
	v_mfma_f32_16x16x32_bf16 v[120:123], v[164:167], v[168:171], v[120:123]
	v_mfma_f32_16x16x32_bf16 v[184:187], v[172:175], v[168:171], v[88:91]
	v_mfma_f32_16x16x32_bf16 v[44:47], v[176:179], v[168:171], v[44:47]
	s_nop 1
	ds_read_b128 v[88:91], v161 offset:18432
	s_waitcnt vmcnt(3)
	ds_write_b128 v163, v[36:39] offset:49152
	s_waitcnt lgkmcnt(3)
	v_mfma_f32_16x16x32_bf16 v[132:135], v[154:157], v[180:183], v[132:135]
	v_mfma_f32_16x16x32_bf16 v[168:171], v[164:167], v[180:183], v[108:111]
	v_mfma_f32_16x16x32_bf16 v[188:191], v[172:175], v[180:183], v[76:79]
	v_mfma_f32_16x16x32_bf16 v[180:183], v[176:179], v[180:183], v[40:43]
	s_nop 2
	ds_read_b128 v[40:43], v161 offset:19968
	s_waitcnt vmcnt(2)
	ds_write_b128 v163, v[32:35] offset:49248
	s_waitcnt lgkmcnt(3)
	v_mfma_f32_16x16x32_bf16 v[124:127], v[154:157], v[88:91], v[124:127]
	v_mfma_f32_16x16x32_bf16 v[192:195], v[164:167], v[88:91], v[96:99]
	v_mfma_f32_16x16x32_bf16 v[196:199], v[172:175], v[88:91], v[64:67]
	v_mfma_f32_16x16x32_bf16 v[200:203], v[176:179], v[88:91], v[12:15]
	s_nop 2
	ds_read_b128 v[12:15], v161 offset:21504
	s_waitcnt vmcnt(1)
	ds_write_b128 v163, v[28:31] offset:49344
	s_waitcnt lgkmcnt(3)
	v_mfma_f32_16x16x32_bf16 v[116:119], v[154:157], v[40:43], v[116:119]
	v_mfma_f32_16x16x32_bf16 v[204:207], v[164:167], v[40:43], v[84:87]
	v_mfma_f32_16x16x32_bf16 v[56:59], v[172:175], v[40:43], v[56:59]
	v_mfma_f32_16x16x32_bf16 v[208:211], v[176:179], v[40:43], v[8:11]
	s_nop 2
	ds_read_b128 v[8:11], v161 offset:23040
	s_waitcnt vmcnt(0)
	ds_write_b128 v163, v[24:27] offset:49440
	s_waitcnt lgkmcnt(3)
	v_mfma_f32_16x16x32_bf16 v[212:215], v[154:157], v[12:15], v[104:107]
	v_mfma_f32_16x16x32_bf16 v[72:75], v[164:167], v[12:15], v[72:75]
	v_mfma_f32_16x16x32_bf16 v[220:223], v[172:175], v[12:15], v[52:55]
	v_mfma_f32_16x16x32_bf16 v[224:227], v[176:179], v[12:15], v[4:7]
	s_waitcnt lgkmcnt(1)
	v_mfma_f32_16x16x32_bf16 v[154:157], v[154:157], v[8:11], v[92:95]
	v_mfma_f32_16x16x32_bf16 v[60:63], v[164:167], v[8:11], v[60:63]
	v_mfma_f32_16x16x32_bf16 v[164:167], v[172:175], v[8:11], v[48:51]
	v_mfma_f32_16x16x32_bf16 v[172:175], v[176:179], v[8:11], v[0:3]
	s_setprio 0
	s_waitcnt lgkmcnt(0)
	s_barrier
; DI void store4(u16* dst, f32x4 v) { uint2 w; w.x = cvtpk(v[0], v[1]); w.y = cvtpk(v[2], v[3]); *(uint2*)dst = w; }
; DI f32x4 mfma16(bf16x8 a, bf16x8 b, f32x4 c) { return __builtin_amdgcn_mfma_f32_16x16x32_bf16(a, b, c, 0, 0, 0); }
; template <int NI, class XL, class EP>
; DI void gemm_tile(const u16* __restrict__ W, int ldw, int f0, int t0, int K, XL xl, EP ep, unsigned char* smem) {
;     ...
;   for (int it = 0; it < nk; ++it) {
;     const u16* Ws = S0 + (it & 1) * BUF; const u16* Xs = Ws + 128 * LST;
;     __builtin_amdgcn_s_setprio(1);
;     bf16x8 a[4];
; #pragma unroll
;     for (int mi = 0; mi < 4; ++mi) a[mi] = *(const bf16x8*)(Ws + (wf * 64 + mi * 16 + lr) * LST + lq * 8);
; #pragma unroll
;     for (int ni = 0; ni < NI; ++ni) {
;       const bf16x8 b = *(const bf16x8*)(Xs + (wt * (NI * 16) + ni * 16 + lr) * LST + lq * 8);
; #pragma unroll
;       for (int mi = 0; mi < 4; ++mi) acc[mi][ni] = mfma16(a[mi], b, acc[mi][ni]);
;     }
;     __builtin_amdgcn_sched_group_barrier(0x100, 6, 0);
; #pragma unroll
;     for (int ni = 0; ni < NI; ++ni) { __builtin_amdgcn_sched_group_barrier(0x008, 4, 0); if (ni + 2 < NI) __builtin_amdgcn_sched_group_barrier(0x100, 1, 0); }
;     __builtin_amdgcn_s_setprio(0);
;     if (it + 1 < nk) lstore((it + 1) & 1);
;     if (it + 2 < nk) gload(it + 2);
;     __syncthreads();
;   }
;   ep(acc, f0 + wf * 64, t0 + wt * (NI * 16), lr, lq, wf, wt);
; DI void phase9(const Params& p, const Sched& sched, unsigned char* smem) {
;     ...
;       constexpr int EST = 136;
;       u16* Ls = (u16*)smem;
;       const int b = tb >> 11;
;       __syncthreads();
; #pragma unroll
;       for (int mi = 0; mi < 4; ++mi) {
;         const int f = fb + mi * 16 + lq * 4; const float4 gm = *(const float4*)(mod + (size_t)b * 6144 + 5120 + f);
; #pragma unroll
;         for (int ni = 0; ni < 8; ++ni) {
;           const f32x4 o = {gm.x * acc[mi][ni][0], gm.y * acc[mi][ni][1], gm.z * acc[mi][ni][2], gm.w * acc[mi][ni][3]};
;           store4(Ls + (wt * 128 + ni * 16 + lr) * EST + wf * 64 + mi * 16 + lq * 4, o);
;         }
	s_lshl_b32 s30, s30, 7
	s_setprio 1
	ds_read_b128 v[28:31], v152 offset:36864
	ds_read_b128 v[176:179], v152 offset:38400
	ds_read_b128 v[228:231], v152 offset:39936
	ds_read_b128 v[232:235], v152 offset:41472
	ds_read_b128 v[0:3], v161 offset:49152
	ds_read_b128 v[4:7], v161 offset:50688
	s_waitcnt lgkmcnt(1)
	v_mfma_f32_16x16x32_bf16 v[88:91], v[28:31], v[0:3], v[148:151]
	v_mfma_f32_16x16x32_bf16 v[64:67], v[176:179], v[0:3], v[136:139]
	v_mfma_f32_16x16x32_bf16 v[32:35], v[228:231], v[0:3], v[112:115]
	v_mfma_f32_16x16x32_bf16 v[0:3], v[232:235], v[0:3], v[80:83]
	ds_read_b128 v[8:11], v161 offset:52224
	s_waitcnt lgkmcnt(1)
	v_mfma_f32_16x16x32_bf16 v[96:99], v[28:31], v[4:7], v[144:147]
	v_mfma_f32_16x16x32_bf16 v[76:79], v[176:179], v[4:7], v[128:131]
	v_mfma_f32_16x16x32_bf16 v[36:39], v[228:231], v[4:7], v[100:103]
	v_mfma_f32_16x16x32_bf16 v[4:7], v[232:235], v[4:7], v[68:71]
	ds_read_b128 v[12:15], v161 offset:53760
	s_waitcnt lgkmcnt(1)
	v_mfma_f32_16x16x32_bf16 v[104:107], v[28:31], v[8:11], v[140:143]
	v_mfma_f32_16x16x32_bf16 v[84:87], v[176:179], v[8:11], v[120:123]
	v_mfma_f32_16x16x32_bf16 v[40:43], v[228:231], v[8:11], v[184:187]
	v_mfma_f32_16x16x32_bf16 v[8:11], v[232:235], v[8:11], v[44:47]
	ds_read_b128 v[16:19], v161 offset:55296
	s_waitcnt lgkmcnt(1)
	v_mfma_f32_16x16x32_bf16 v[108:111], v[28:31], v[12:15], v[132:135]
	v_mfma_f32_16x16x32_bf16 v[92:95], v[176:179], v[12:15], v[168:171]
	v_mfma_f32_16x16x32_bf16 v[44:47], v[228:231], v[12:15], v[188:191]
	v_mfma_f32_16x16x32_bf16 v[12:15], v[232:235], v[12:15], v[180:183]
	ds_read_b128 v[20:23], v161 offset:56832
	s_waitcnt lgkmcnt(1)
	v_mfma_f32_16x16x32_bf16 v[112:115], v[28:31], v[16:19], v[124:127]
	v_mfma_f32_16x16x32_bf16 v[100:103], v[176:179], v[16:19], v[192:195]
	v_mfma_f32_16x16x32_bf16 v[48:51], v[228:231], v[16:19], v[196:199]
	v_mfma_f32_16x16x32_bf16 v[16:19], v[232:235], v[16:19], v[200:203]
	ds_read_b128 v[24:27], v161 offset:58368
	s_waitcnt lgkmcnt(1)
	v_mfma_f32_16x16x32_bf16 v[116:119], v[28:31], v[20:23], v[116:119]
	v_mfma_f32_16x16x32_bf16 v[68:71], v[176:179], v[20:23], v[204:207]
	v_mfma_f32_16x16x32_bf16 v[52:55], v[228:231], v[20:23], v[56:59]
	v_mfma_f32_16x16x32_bf16 v[20:23], v[232:235], v[20:23], v[208:211]
	ds_read_b128 v[128:131], v161 offset:59904
	s_waitcnt lgkmcnt(1)
	v_mfma_f32_16x16x32_bf16 v[120:123], v[28:31], v[24:27], v[212:215]
	v_mfma_f32_16x16x32_bf16 v[80:83], v[176:179], v[24:27], v[72:75]
	v_mfma_f32_16x16x32_bf16 v[56:59], v[228:231], v[24:27], v[220:223]
	v_mfma_f32_16x16x32_bf16 v[24:27], v[232:235], v[24:27], v[224:227]
	s_waitcnt lgkmcnt(0)
	v_mfma_f32_16x16x32_bf16 v[124:127], v[28:31], v[128:131], v[154:157]
	v_mfma_f32_16x16x32_bf16 v[72:75], v[176:179], v[128:131], v[60:63]
	v_mfma_f32_16x16x32_bf16 v[60:63], v[228:231], v[128:131], v[164:167]
	v_mfma_f32_16x16x32_bf16 v[28:31], v[232:235], v[128:131], v[172:175]
	s_setprio 0
	s_ashr_i32 s31, s31, 3
	v_add_u32_e32 v128, s30, v160
	s_mul_hi_i32 s33, s31, 0x6000
	s_mulk_i32 s31, 0x6000
	v_lshl_or_b32 v128, v158, 2, v128
	s_add_u32 s34, s72, s31
	s_addc_u32 s35, s73, s33
	v_ashrrev_i32_e32 v129, 31, v128
	v_lshl_add_u64 v[128:129], v[128:129], 2, s[34:35]
	v_add_co_u32_e32 v140, vcc, s24, v128
	v_mul_u32_u24_e32 v138, 0x88, v159
	s_nop 0
	v_addc_co_u32_e32 v141, vcc, 0, v129, vcc
	v_lshlrev_b32_e32 v136, 1, v160
	v_lshlrev_b32_e32 v137, 3, v158
	v_lshlrev_b32_e32 v138, 1, v138
	s_barrier
	global_load_dwordx4 v[128:131], v[140:141], off
	global_load_dwordx4 v[132:135], v[140:141], off offset:64
	v_add3_u32 v144, v136, v137, v138
	global_load_dwordx4 v[136:139], v[140:141], off offset:128
	v_add_u32_e32 v145, 0x1000, v144
	global_load_dwordx4 v[140:143], v[140:141], off offset:192
	v_add_u32_e32 v146, 0x2000, v144
	v_add_u32_e32 v147, 0x3000, v144
	v_add_u32_e32 v148, 0x4000, v144
	s_waitcnt vmcnt(3)
	v_pk_mul_f32 v[88:89], v[88:89], v[128:129]
	v_pk_mul_f32 v[90:91], v[90:91], v[130:131]
	v_pk_mul_f32 v[96:97], v[96:97], v[128:129]
	s_waitcnt vmcnt(1)
	v_pk_mul_f32 v[32:33], v[32:33], v[136:137]
	v_pk_mul_f32 v[34:35], v[34:35], v[138:139]
	s_waitcnt vmcnt(0)
	v_pk_mul_f32 v[0:1], v[0:1], v[140:141]
	v_pk_mul_f32 v[2:3], v[2:3], v[142:143]
	v_cvt_pk_bf16_f32 v32, v32, v33
	v_cvt_pk_bf16_f32 v33, v34, v35
	v_cvt_pk_bf16_f32 v0, v0, v1
	v_cvt_pk_bf16_f32 v1, v2, v3
	v_pk_mul_f32 v[34:35], v[36:37], v[136:137]
	v_pk_mul_f32 v[36:37], v[38:39], v[138:139]
	ds_write2_b64 v144, v[32:33], v[0:1] offset0:8 offset1:12
	v_pk_mul_f32 v[0:1], v[4:5], v[140:141]
	v_pk_mul_f32 v[2:3], v[6:7], v[142:143]
	v_cvt_pk_bf16_f32 v34, v34, v35
	v_cvt_pk_bf16_f32 v35, v36, v37
	v_cvt_pk_bf16_f32 v0, v0, v1
	v_cvt_pk_bf16_f32 v1, v2, v3
	v_pk_mul_f32 v[36:37], v[40:41], v[136:137]
	v_pk_mul_f32 v[38:39], v[42:43], v[138:139]
	ds_write2_b64 v145, v[34:35], v[0:1] offset0:40 offset1:44
	v_pk_mul_f32 v[0:1], v[8:9], v[140:141]
	v_pk_mul_f32 v[2:3], v[10:11], v[142:143]
	v_cvt_pk_bf16_f32 v36, v36, v37
	v_cvt_pk_bf16_f32 v37, v38, v39
	v_cvt_pk_bf16_f32 v0, v0, v1
	v_cvt_pk_bf16_f32 v1, v2, v3
	v_pk_mul_f32 v[38:39], v[44:45], v[136:137]
	v_pk_mul_f32 v[40:41], v[46:47], v[138:139]
	ds_write2_b64 v146, v[36:37], v[0:1] offset0:72 offset1:76
	v_pk_mul_f32 v[0:1], v[12:13], v[140:141]
	v_pk_mul_f32 v[2:3], v[14:15], v[142:143]
	v_cvt_pk_bf16_f32 v38, v38, v39
	v_cvt_pk_bf16_f32 v39, v40, v41
	v_cvt_pk_bf16_f32 v0, v0, v1
	v_cvt_pk_bf16_f32 v1, v2, v3
	v_pk_mul_f32 v[98:99], v[98:99], v[130:131]
	v_pk_mul_f32 v[64:65], v[64:65], v[132:133]
	v_pk_mul_f32 v[66:67], v[66:67], v[134:135]
	v_pk_mul_f32 v[76:77], v[76:77], v[132:133]
	v_pk_mul_f32 v[78:79], v[78:79], v[134:135]
; DI void store4(u16* dst, f32x4 v) { uint2 w; w.x = cvtpk(v[0], v[1]); w.y = cvtpk(v[2], v[3]); *(uint2*)dst = w; }
; DI void phase9(const Params& p, const Sched& sched, unsigned char* smem) {
;     ...
;       __syncthreads();
; #pragma unroll
;       for (int mi = 0; mi < 4; ++mi) {
;         const int f = fb + mi * 16 + lq * 4; const float4 gm = *(const float4*)(mod + (size_t)b * 6144 + 5120 + f);
; #pragma unroll
;         for (int ni = 0; ni < 8; ++ni) {
;           const f32x4 o = {gm.x * acc[mi][ni][0], gm.y * acc[mi][ni][1], gm.z * acc[mi][ni][2], gm.w * acc[mi][ni][3]};
;           store4(Ls + (wt * 128 + ni * 16 + lr) * EST + wf * 64 + mi * 16 + lq * 4, o);
;         }
;       }
	v_pk_mul_f32 v[40:41], v[48:49], v[136:137]
	v_pk_mul_f32 v[42:43], v[50:51], v[138:139]
	ds_write2_b64 v147, v[38:39], v[0:1] offset0:104 offset1:108
	v_pk_mul_f32 v[0:1], v[16:17], v[140:141]
	v_pk_mul_f32 v[2:3], v[18:19], v[142:143]
	v_cvt_pk_bf16_f32 v88, v88, v89
	v_cvt_pk_bf16_f32 v89, v90, v91
	v_cvt_pk_bf16_f32 v90, v96, v97
	v_cvt_pk_bf16_f32 v91, v98, v99
	v_cvt_pk_bf16_f32 v64, v64, v65
	v_cvt_pk_bf16_f32 v65, v66, v67
	v_cvt_pk_bf16_f32 v66, v76, v77
	v_cvt_pk_bf16_f32 v67, v78, v79
	v_cvt_pk_bf16_f32 v40, v40, v41
	v_cvt_pk_bf16_f32 v41, v42, v43
	v_cvt_pk_bf16_f32 v0, v0, v1
	v_cvt_pk_bf16_f32 v1, v2, v3
	v_pk_mul_f32 v[106:107], v[106:107], v[130:131]
	v_pk_mul_f32 v[116:117], v[116:117], v[128:129]
	v_pk_mul_f32 v[118:119], v[118:119], v[130:131]
	ds_write2_b64 v144, v[88:89], v[64:65] offset1:4
	ds_write2_b64 v145, v[90:91], v[66:67] offset0:32 offset1:36
	v_pk_mul_f32 v[64:65], v[68:69], v[132:133]
	v_pk_mul_f32 v[66:67], v[70:71], v[134:135]
	v_pk_mul_f32 v[42:43], v[52:53], v[136:137]
	v_pk_mul_f32 v[44:45], v[54:55], v[138:139]
	ds_write2_b64 v148, v[40:41], v[0:1] offset0:136 offset1:140
	v_pk_mul_f32 v[0:1], v[20:21], v[140:141]
	v_pk_mul_f32 v[2:3], v[22:23], v[142:143]
	v_cvt_pk_bf16_f32 v97, v106, v107
	v_cvt_pk_bf16_f32 v106, v116, v117
	v_cvt_pk_bf16_f32 v107, v118, v119
	v_cvt_pk_bf16_f32 v64, v64, v65
	v_cvt_pk_bf16_f32 v65, v66, v67
	v_add_u32_e32 v68, 0x5000, v144
	v_cvt_pk_bf16_f32 v42, v42, v43
	v_cvt_pk_bf16_f32 v43, v44, v45
	v_cvt_pk_bf16_f32 v0, v0, v1
	v_cvt_pk_bf16_f32 v1, v2, v3
	v_pk_mul_f32 v[108:109], v[108:109], v[128:129]
	v_pk_mul_f32 v[120:121], v[120:121], v[128:129]
	v_pk_mul_f32 v[122:123], v[122:123], v[130:131]
	ds_write2_b64 v68, v[106:107], v[64:65] offset0:160 offset1:164
	v_pk_mul_f32 v[64:65], v[80:81], v[132:133]
	v_pk_mul_f32 v[66:67], v[82:83], v[134:135]
	v_pk_mul_f32 v[44:45], v[56:57], v[136:137]
	v_pk_mul_f32 v[46:47], v[58:59], v[138:139]
	ds_write2_b64 v68, v[42:43], v[0:1] offset0:168 offset1:172
	v_pk_mul_f32 v[0:1], v[24:25], v[140:141]
	v_pk_mul_f32 v[2:3], v[26:27], v[142:143]
	v_cvt_pk_bf16_f32 v98, v108, v109
	v_cvt_pk_bf16_f32 v108, v120, v121
	v_cvt_pk_bf16_f32 v109, v122, v123
	v_cvt_pk_bf16_f32 v64, v64, v65
	v_cvt_pk_bf16_f32 v65, v66, v67
	v_add_u32_e32 v69, 0x6000, v144
	v_cvt_pk_bf16_f32 v44, v44, v45
	v_cvt_pk_bf16_f32 v45, v46, v47
	v_cvt_pk_bf16_f32 v0, v0, v1
	v_cvt_pk_bf16_f32 v1, v2, v3
	v_pk_mul_f32 v[104:105], v[104:105], v[128:129]
	v_pk_mul_f32 v[110:111], v[110:111], v[130:131]
	v_pk_mul_f32 v[112:113], v[112:113], v[128:129]
	v_pk_mul_f32 v[114:115], v[114:115], v[130:131]
	v_pk_mul_f32 v[124:125], v[124:125], v[128:129]
	v_pk_mul_f32 v[126:127], v[126:127], v[130:131]
	v_pk_mul_f32 v[84:85], v[84:85], v[132:133]
	v_pk_mul_f32 v[86:87], v[86:87], v[134:135]
	v_pk_mul_f32 v[92:93], v[92:93], v[132:133]
	v_pk_mul_f32 v[94:95], v[94:95], v[134:135]
	v_pk_mul_f32 v[100:101], v[100:101], v[132:133]
	v_pk_mul_f32 v[102:103], v[102:103], v[134:135]
	ds_write2_b64 v69, v[108:109], v[64:65] offset0:192 offset1:196
	v_pk_mul_f32 v[64:65], v[72:73], v[132:133]
	v_pk_mul_f32 v[66:67], v[74:75], v[134:135]
	v_pk_mul_f32 v[46:47], v[60:61], v[136:137]
	v_pk_mul_f32 v[48:49], v[62:63], v[138:139]
	ds_write2_b64 v69, v[44:45], v[0:1] offset0:200 offset1:204
	v_pk_mul_f32 v[0:1], v[28:29], v[140:141]
	v_pk_mul_f32 v[2:3], v[30:31], v[142:143]
	v_cvt_pk_bf16_f32 v96, v104, v105
	v_cvt_pk_bf16_f32 v99, v110, v111
	v_cvt_pk_bf16_f32 v104, v112, v113
	v_cvt_pk_bf16_f32 v105, v114, v115
	v_cvt_pk_bf16_f32 v110, v124, v125
	v_cvt_pk_bf16_f32 v111, v126, v127
	v_cvt_pk_bf16_f32 v76, v84, v85
	v_cvt_pk_bf16_f32 v77, v86, v87
	v_cvt_pk_bf16_f32 v78, v92, v93
	v_cvt_pk_bf16_f32 v79, v94, v95
	v_cvt_pk_bf16_f32 v84, v100, v101
	v_cvt_pk_bf16_f32 v85, v102, v103
	v_cvt_pk_bf16_f32 v64, v64, v65
	v_cvt_pk_bf16_f32 v65, v66, v67
	v_add_u32_e32 v66, 0x7000, v144
	v_cvt_pk_bf16_f32 v46, v46, v47
	v_cvt_pk_bf16_f32 v47, v48, v49
	v_cvt_pk_bf16_f32 v0, v0, v1
	v_cvt_pk_bf16_f32 v1, v2, v3
	v_mov_b32_e32 v2, v218
	ds_write2_b64 v146, v[96:97], v[76:77] offset0:64 offset1:68
	ds_write2_b64 v147, v[98:99], v[78:79] offset0:96 offset1:100
	ds_write2_b64 v148, v[104:105], v[84:85] offset0:128 offset1:132
	ds_write2_b64 v66, v[110:111], v[64:65] offset0:224 offset1:228
	ds_write2_b64 v66, v[46:47], v[0:1] offset0:232 offset1:236
	s_waitcnt lgkmcnt(0)
	s_barrier
; DI int tidx() { int t = __builtin_amdgcn_workitem_id_x(); asm volatile("" : "+v"(t)); return t; }
; DI unsigned cvtpk(float lo, float hi) { const f32x2_ v = {lo, hi}; return __builtin_bit_cast(unsigned, __builtin_convertvector(v, bf16x2_)); }
; DI float bflo(unsigned w) { return __uint_as_float(w << 16); }
; DI float bfhi(unsigned w) { return __uint_as_float(w & 0xffff0000u); }
; DI void phase9(const Params& p, const Sched& sched, unsigned char* smem) {
;     ...
;       __syncthreads();
;       const int tid = tidx();
; #pragma unroll
;       for (int i = 0; i < 16; ++i) {
;         const int c = tid + 256 * i, row = c >> 4, ch = (c & 15) * 8;
;         const size_t gi = (size_t)(tm * 256 + row) * 1024 + tn * 128 + ch;
;         const u32x4 sv = *(const u32x4*)(Ls + row * EST + ch), xv = *(const u32x4*)(x1b + gi);
;         u32x4 w;
;         w.x = cvtpk(bflo(xv.x) + bflo(sv.x), bfhi(xv.x) + bfhi(sv.x)); w.y = cvtpk(bflo(xv.y) + bflo(sv.y), bfhi(xv.y) + bfhi(sv.y));
;         w.z = cvtpk(bflo(xv.z) + bflo(sv.z), bfhi(xv.z) + bfhi(sv.z)); w.w = cvtpk(bflo(xv.w) + bflo(sv.w), bfhi(xv.w) + bfhi(sv.w));
;         *(u32x4*)(x2b + gi) = w;
;       }
	s_nop 0
	v_ashrrev_i32_e32 v3, 4, v2
	v_add_u32_e32 v4, s29, v3
	v_lshlrev_b32_e32 v0, 3, v2
	v_ashrrev_i32_e32 v5, 31, v4
	v_and_b32_e32 v1, 0x78, v0
	v_lshlrev_b64 v[4:5], 10, v[4:5]
	v_or3_b32 v4, v4, s30, v1
	v_lshlrev_b64 v[12:13], 1, v[4:5]
	v_lshl_add_u64 v[4:5], s[12:13], 0, v[12:13]
	global_load_dwordx4 v[4:7], v[4:5], off
	v_lshlrev_b32_e32 v0, 1, v1
	v_mad_u64_u32 v[8:9], s[34:35], v3, s25, v[0:1]
	ds_read_b128 v[8:11], v8
	v_add_u32_e32 v3, 0x100, v2
	v_ashrrev_i32_e32 v3, 4, v3
	s_waitcnt lgkmcnt(0)
	v_lshlrev_b32_e32 v16, 16, v8
	v_and_b32_e32 v17, 0xffff0000, v8
	v_lshlrev_b32_e32 v8, 16, v9
	v_and_b32_e32 v9, 0xffff0000, v9
	s_waitcnt vmcnt(0)
	v_lshlrev_b32_e32 v14, 16, v4
	v_and_b32_e32 v15, 0xffff0000, v4
	v_pk_add_f32 v[14:15], v[16:17], v[14:15]
	s_nop 0
	v_cvt_pk_bf16_f32 v4, v14, v15
	v_lshlrev_b32_e32 v14, 16, v5
	v_and_b32_e32 v15, 0xffff0000, v5
	v_pk_add_f32 v[8:9], v[8:9], v[14:15]
	v_lshlrev_b32_e32 v14, 16, v10
	v_cvt_pk_bf16_f32 v5, v8, v9
	v_lshlrev_b32_e32 v8, 16, v6
	v_and_b32_e32 v9, 0xffff0000, v6
	v_and_b32_e32 v15, 0xffff0000, v10
	v_pk_add_f32 v[8:9], v[14:15], v[8:9]
	v_lshlrev_b32_e32 v10, 16, v11
	v_cvt_pk_bf16_f32 v6, v8, v9
	v_lshlrev_b32_e32 v8, 16, v7
	v_and_b32_e32 v9, 0xffff0000, v7
	v_and_b32_e32 v11, 0xffff0000, v11
	v_pk_add_f32 v[8:9], v[10:11], v[8:9]
	s_nop 0
	v_cvt_pk_bf16_f32 v7, v8, v9
	v_lshl_add_u64 v[8:9], s[2:3], 0, v[12:13]
	global_store_dwordx4 v[8:9], v[4:7], off
	v_mad_u64_u32 v[8:9], s[34:35], v3, s25, v[0:1]
	s_nop 0
	v_add_u32_e32 v4, s29, v3
	v_ashrrev_i32_e32 v5, 31, v4
	v_lshlrev_b64 v[4:5], 10, v[4:5]
	v_or3_b32 v4, v4, s30, v1
	v_lshlrev_b64 v[12:13], 1, v[4:5]
	v_lshl_add_u64 v[4:5], s[12:13], 0, v[12:13]
	global_load_dwordx4 v[4:7], v[4:5], off
	ds_read_b128 v[8:11], v8
	v_add_u32_e32 v3, 0x200, v2
	v_ashrrev_i32_e32 v3, 4, v3
	v_lshl_add_u64 v[12:13], s[2:3], 0, v[12:13]
	s_waitcnt lgkmcnt(0)
	v_lshlrev_b32_e32 v14, 16, v8
	v_and_b32_e32 v15, 0xffff0000, v8
	v_lshlrev_b32_e32 v8, 16, v9
	v_and_b32_e32 v9, 0xffff0000, v9
	v_lshlrev_b32_e32 v16, 16, v10
	v_and_b32_e32 v17, 0xffff0000, v10
	v_lshlrev_b32_e32 v10, 16, v11
	v_and_b32_e32 v11, 0xffff0000, v11
	s_waitcnt vmcnt(0)
	v_lshlrev_b32_e32 v18, 16, v4
	v_and_b32_e32 v19, 0xffff0000, v4
	v_lshlrev_b32_e32 v4, 16, v5
	v_and_b32_e32 v5, 0xffff0000, v5
	v_lshlrev_b32_e32 v20, 16, v6
	v_and_b32_e32 v21, 0xffff0000, v6
	v_lshlrev_b32_e32 v6, 16, v7
	v_and_b32_e32 v7, 0xffff0000, v7
	v_pk_add_f32 v[14:15], v[14:15], v[18:19]
	v_pk_add_f32 v[8:9], v[8:9], v[4:5]
	v_pk_add_f32 v[16:17], v[16:17], v[20:21]
	v_pk_add_f32 v[10:11], v[10:11], v[6:7]
	v_cvt_pk_bf16_f32 v4, v14, v15
	v_cvt_pk_bf16_f32 v5, v8, v9
	v_cvt_pk_bf16_f32 v6, v16, v17
	v_cvt_pk_bf16_f32 v7, v10, v11
	global_store_dwordx4 v[12:13], v[4:7], off
	v_add_u32_e32 v8, 0x300, v2
	v_ashrrev_i32_e32 v26, 4, v8
	v_add_u32_e32 v4, s29, v3
	v_ashrrev_i32_e32 v5, 31, v4
	v_lshlrev_b64 v[4:5], 10, v[4:5]
	v_or3_b32 v4, v4, s30, v1
	v_lshlrev_b64 v[12:13], 1, v[4:5]
	v_lshl_add_u64 v[4:5], s[12:13], 0, v[12:13]
	global_load_dwordx4 v[4:7], v[4:5], off
	v_mad_u64_u32 v[8:9], s[34:35], v3, s25, v[0:1]
	ds_read_b128 v[8:11], v8
	v_add_u32_e32 v14, s29, v26
	v_ashrrev_i32_e32 v15, 31, v14
	v_lshlrev_b64 v[14:15], 10, v[14:15]
	v_or3_b32 v14, v14, s30, v1
	s_waitcnt lgkmcnt(0)
	v_lshlrev_b32_e32 v18, 16, v8
	v_and_b32_e32 v19, 0xffff0000, v8
	v_lshlrev_b32_e32 v8, 16, v9
	v_and_b32_e32 v9, 0xffff0000, v9
	v_lshlrev_b32_e32 v20, 16, v10
	v_and_b32_e32 v21, 0xffff0000, v10
	v_lshlrev_b32_e32 v10, 16, v11
	v_and_b32_e32 v11, 0xffff0000, v11
	v_lshlrev_b64 v[14:15], 1, v[14:15]
	v_lshl_add_u64 v[12:13], s[2:3], 0, v[12:13]
	v_lshl_add_u64 v[16:17], s[12:13], 0, v[14:15]
	v_add_u32_e32 v3, 0x400, v2
	v_ashrrev_i32_e32 v3, 4, v3
	v_lshl_add_u64 v[14:15], s[2:3], 0, v[14:15]
	s_waitcnt vmcnt(0)
	v_lshlrev_b32_e32 v22, 16, v4
	v_and_b32_e32 v23, 0xffff0000, v4
	v_lshlrev_b32_e32 v4, 16, v5
	v_and_b32_e32 v5, 0xffff0000, v5
	v_lshlrev_b32_e32 v24, 16, v6
	v_and_b32_e32 v25, 0xffff0000, v6
	v_lshlrev_b32_e32 v6, 16, v7
	v_and_b32_e32 v7, 0xffff0000, v7
	v_pk_add_f32 v[18:19], v[18:19], v[22:23]
	v_pk_add_f32 v[8:9], v[8:9], v[4:5]
	v_pk_add_f32 v[20:21], v[20:21], v[24:25]
	v_pk_add_f32 v[10:11], v[10:11], v[6:7]
	v_cvt_pk_bf16_f32 v4, v18, v19
	v_cvt_pk_bf16_f32 v5, v8, v9
	v_cvt_pk_bf16_f32 v6, v20, v21
	v_cvt_pk_bf16_f32 v7, v10, v11
	global_store_dwordx4 v[12:13], v[4:7], off
	global_load_dwordx4 v[4:7], v[16:17], off
	v_mad_u64_u32 v[8:9], s[34:35], v26, s25, v[0:1]
	ds_read_b128 v[8:11], v8
	v_add_u32_e32 v12, s29, v3
	v_ashrrev_i32_e32 v13, 31, v12
	v_lshlrev_b64 v[12:13], 10, v[12:13]
	v_or3_b32 v12, v12, s30, v1
	s_waitcnt lgkmcnt(0)
	v_lshlrev_b32_e32 v18, 16, v8
	v_and_b32_e32 v19, 0xffff0000, v8
	v_lshlrev_b32_e32 v8, 16, v9
	v_and_b32_e32 v9, 0xffff0000, v9
	v_lshlrev_b32_e32 v20, 16, v10
	v_and_b32_e32 v21, 0xffff0000, v10
	v_lshlrev_b32_e32 v10, 16, v11
	v_and_b32_e32 v11, 0xffff0000, v11
	v_lshlrev_b64 v[12:13], 1, v[12:13]
	v_lshl_add_u64 v[16:17], s[12:13], 0, v[12:13]
	v_lshl_add_u64 v[12:13], s[2:3], 0, v[12:13]
	s_waitcnt vmcnt(0)
	v_lshlrev_b32_e32 v22, 16, v4
	v_and_b32_e32 v23, 0xffff0000, v4
	v_lshlrev_b32_e32 v4, 16, v5
	v_and_b32_e32 v5, 0xffff0000, v5
	v_lshlrev_b32_e32 v24, 16, v6
	v_and_b32_e32 v25, 0xffff0000, v6
	v_lshlrev_b32_e32 v6, 16, v7
	v_and_b32_e32 v7, 0xffff0000, v7
	v_pk_add_f32 v[18:19], v[18:19], v[22:23]
	v_pk_add_f32 v[8:9], v[8:9], v[4:5]
	v_pk_add_f32 v[20:21], v[20:21], v[24:25]
	v_pk_add_f32 v[10:11], v[10:11], v[6:7]
	v_cvt_pk_bf16_f32 v4, v18, v19
	v_cvt_pk_bf16_f32 v5, v8, v9
	v_cvt_pk_bf16_f32 v6, v20, v21
	v_cvt_pk_bf16_f32 v7, v10, v11
	global_store_dwordx4 v[14:15], v[4:7], off
	global_load_dwordx4 v[4:7], v[16:17], off
	v_add_u32_e32 v8, 0x500, v2
	v_ashrrev_i32_e32 v26, 4, v8
	v_mad_u64_u32 v[8:9], s[34:35], v3, s25, v[0:1]
	ds_read_b128 v[8:11], v8
	v_add_u32_e32 v14, s29, v26
	v_ashrrev_i32_e32 v15, 31, v14
	v_lshlrev_b64 v[14:15], 10, v[14:15]
	v_or3_b32 v14, v14, s30, v1
	s_waitcnt lgkmcnt(0)
; DI unsigned cvtpk(float lo, float hi) { const f32x2_ v = {lo, hi}; return __builtin_bit_cast(unsigned, __builtin_convertvector(v, bf16x2_)); }
; DI float bflo(unsigned w) { return __uint_as_float(w << 16); }
; DI float bfhi(unsigned w) { return __uint_as_float(w & 0xffff0000u); }
; DI void phase9(const Params& p, const Sched& sched, unsigned char* smem) {
;     ...
; #pragma unroll
;       for (int i = 0; i < 16; ++i) {
;         const int c = tid + 256 * i, row = c >> 4, ch = (c & 15) * 8;
;         const size_t gi = (size_t)(tm * 256 + row) * 1024 + tn * 128 + ch;
;         const u32x4 sv = *(const u32x4*)(Ls + row * EST + ch), xv = *(const u32x4*)(x1b + gi);
;         u32x4 w;
;         w.x = cvtpk(bflo(xv.x) + bflo(sv.x), bfhi(xv.x) + bfhi(sv.x)); w.y = cvtpk(bflo(xv.y) + bflo(sv.y), bfhi(xv.y) + bfhi(sv.y));
;         w.z = cvtpk(bflo(xv.z) + bflo(sv.z), bfhi(xv.z) + bfhi(sv.z)); w.w = cvtpk(bflo(xv.w) + bflo(sv.w), bfhi(xv.w) + bfhi(sv.w));
;         *(u32x4*)(x2b + gi) = w;
;       }
	v_lshlrev_b32_e32 v18, 16, v8
	v_and_b32_e32 v19, 0xffff0000, v8
	v_lshlrev_b32_e32 v8, 16, v9
	v_and_b32_e32 v9, 0xffff0000, v9
	v_lshlrev_b32_e32 v20, 16, v10
	v_and_b32_e32 v21, 0xffff0000, v10
	v_lshlrev_b32_e32 v10, 16, v11
	v_and_b32_e32 v11, 0xffff0000, v11
	v_lshlrev_b64 v[14:15], 1, v[14:15]
	v_lshl_add_u64 v[16:17], s[12:13], 0, v[14:15]
	v_add_u32_e32 v3, 0x600, v2
	v_ashrrev_i32_e32 v3, 4, v3
	v_lshl_add_u64 v[14:15], s[2:3], 0, v[14:15]
	s_waitcnt vmcnt(0)
	v_lshlrev_b32_e32 v22, 16, v4
	v_and_b32_e32 v23, 0xffff0000, v4
	v_lshlrev_b32_e32 v4, 16, v5
	v_and_b32_e32 v5, 0xffff0000, v5
	v_lshlrev_b32_e32 v24, 16, v6
	v_and_b32_e32 v25, 0xffff0000, v6
	v_lshlrev_b32_e32 v6, 16, v7
	v_and_b32_e32 v7, 0xffff0000, v7
	v_pk_add_f32 v[18:19], v[18:19], v[22:23]
	v_pk_add_f32 v[8:9], v[8:9], v[4:5]
	v_pk_add_f32 v[20:21], v[20:21], v[24:25]
	v_pk_add_f32 v[10:11], v[10:11], v[6:7]
	v_cvt_pk_bf16_f32 v4, v18, v19
	v_cvt_pk_bf16_f32 v5, v8, v9
	v_cvt_pk_bf16_f32 v6, v20, v21
	v_cvt_pk_bf16_f32 v7, v10, v11
	global_store_dwordx4 v[12:13], v[4:7], off
	global_load_dwordx4 v[4:7], v[16:17], off
	v_mad_u64_u32 v[8:9], s[34:35], v26, s25, v[0:1]
	ds_read_b128 v[8:11], v8
	v_add_u32_e32 v12, s29, v3
	v_ashrrev_i32_e32 v13, 31, v12
	v_lshlrev_b64 v[12:13], 10, v[12:13]
	v_or3_b32 v12, v12, s30, v1
	s_waitcnt lgkmcnt(0)
	v_lshlrev_b32_e32 v18, 16, v8
	v_and_b32_e32 v19, 0xffff0000, v8
	v_lshlrev_b32_e32 v8, 16, v9
	v_and_b32_e32 v9, 0xffff0000, v9
	v_lshlrev_b32_e32 v20, 16, v10
	v_and_b32_e32 v21, 0xffff0000, v10
	v_lshlrev_b32_e32 v10, 16, v11
	v_and_b32_e32 v11, 0xffff0000, v11
	v_lshlrev_b64 v[12:13], 1, v[12:13]
	v_lshl_add_u64 v[16:17], s[12:13], 0, v[12:13]
	v_lshl_add_u64 v[12:13], s[2:3], 0, v[12:13]
	s_waitcnt vmcnt(0)
	v_lshlrev_b32_e32 v22, 16, v4
	v_and_b32_e32 v23, 0xffff0000, v4
	v_lshlrev_b32_e32 v4, 16, v5
	v_and_b32_e32 v5, 0xffff0000, v5
	v_lshlrev_b32_e32 v24, 16, v6
	v_and_b32_e32 v25, 0xffff0000, v6
	v_lshlrev_b32_e32 v6, 16, v7
	v_and_b32_e32 v7, 0xffff0000, v7
	v_pk_add_f32 v[18:19], v[18:19], v[22:23]
	v_pk_add_f32 v[8:9], v[8:9], v[4:5]
	v_pk_add_f32 v[20:21], v[20:21], v[24:25]
	v_pk_add_f32 v[10:11], v[10:11], v[6:7]
	v_cvt_pk_bf16_f32 v4, v18, v19
	v_cvt_pk_bf16_f32 v5, v8, v9
	v_cvt_pk_bf16_f32 v6, v20, v21
	v_cvt_pk_bf16_f32 v7, v10, v11
	global_store_dwordx4 v[14:15], v[4:7], off
	global_load_dwordx4 v[4:7], v[16:17], off
	v_add_u32_e32 v8, 0x700, v2
	v_ashrrev_i32_e32 v26, 4, v8
	v_mad_u64_u32 v[8:9], s[34:35], v3, s25, v[0:1]
	ds_read_b128 v[8:11], v8
	v_add_u32_e32 v14, s29, v26
	v_ashrrev_i32_e32 v15, 31, v14
	v_lshlrev_b64 v[14:15], 10, v[14:15]
	v_or3_b32 v14, v14, s30, v1
	s_waitcnt lgkmcnt(0)
	v_lshlrev_b32_e32 v18, 16, v8
	v_and_b32_e32 v19, 0xffff0000, v8
	v_lshlrev_b32_e32 v8, 16, v9
	v_and_b32_e32 v9, 0xffff0000, v9
	v_lshlrev_b32_e32 v20, 16, v10
	v_and_b32_e32 v21, 0xffff0000, v10
	v_lshlrev_b32_e32 v10, 16, v11
	v_and_b32_e32 v11, 0xffff0000, v11
	v_lshlrev_b64 v[14:15], 1, v[14:15]
	v_lshl_add_u64 v[16:17], s[12:13], 0, v[14:15]
	v_add_u32_e32 v3, 0x800, v2
	v_ashrrev_i32_e32 v3, 4, v3
	v_lshl_add_u64 v[14:15], s[2:3], 0, v[14:15]
	s_waitcnt vmcnt(0)
	v_lshlrev_b32_e32 v22, 16, v4
	v_and_b32_e32 v23, 0xffff0000, v4
	v_lshlrev_b32_e32 v4, 16, v5
	v_and_b32_e32 v5, 0xffff0000, v5
	v_lshlrev_b32_e32 v24, 16, v6
	v_and_b32_e32 v25, 0xffff0000, v6
	v_lshlrev_b32_e32 v6, 16, v7
	v_and_b32_e32 v7, 0xffff0000, v7
	v_pk_add_f32 v[18:19], v[18:19], v[22:23]
	v_pk_add_f32 v[8:9], v[8:9], v[4:5]
	v_pk_add_f32 v[20:21], v[20:21], v[24:25]
	v_pk_add_f32 v[10:11], v[10:11], v[6:7]
	v_cvt_pk_bf16_f32 v4, v18, v19
	v_cvt_pk_bf16_f32 v5, v8, v9
	v_cvt_pk_bf16_f32 v6, v20, v21
	v_cvt_pk_bf16_f32 v7, v10, v11
	global_store_dwordx4 v[12:13], v[4:7], off
	global_load_dwordx4 v[4:7], v[16:17], off
	v_mad_u64_u32 v[8:9], s[34:35], v26, s25, v[0:1]
	ds_read_b128 v[8:11], v8
	v_add_u32_e32 v12, s29, v3
	v_ashrrev_i32_e32 v13, 31, v12
	v_lshlrev_b64 v[12:13], 10, v[12:13]
	v_or3_b32 v12, v12, s30, v1
	s_waitcnt lgkmcnt(0)
	v_lshlrev_b32_e32 v18, 16, v8
	v_and_b32_e32 v19, 0xffff0000, v8
	v_lshlrev_b32_e32 v8, 16, v9
	v_and_b32_e32 v9, 0xffff0000, v9
	v_lshlrev_b32_e32 v20, 16, v10
	v_and_b32_e32 v21, 0xffff0000, v10
	v_lshlrev_b32_e32 v10, 16, v11
	v_and_b32_e32 v11, 0xffff0000, v11
	v_lshlrev_b64 v[12:13], 1, v[12:13]
	v_lshl_add_u64 v[16:17], s[12:13], 0, v[12:13]
	v_lshl_add_u64 v[12:13], s[2:3], 0, v[12:13]
	s_waitcnt vmcnt(0)
	v_lshlrev_b32_e32 v22, 16, v4
	v_and_b32_e32 v23, 0xffff0000, v4
	v_lshlrev_b32_e32 v4, 16, v5
	v_and_b32_e32 v5, 0xffff0000, v5
	v_lshlrev_b32_e32 v24, 16, v6
	v_and_b32_e32 v25, 0xffff0000, v6
	v_lshlrev_b32_e32 v6, 16, v7
	v_and_b32_e32 v7, 0xffff0000, v7
	v_pk_add_f32 v[18:19], v[18:19], v[22:23]
	v_pk_add_f32 v[8:9], v[8:9], v[4:5]
	v_pk_add_f32 v[20:21], v[20:21], v[24:25]
	v_pk_add_f32 v[10:11], v[10:11], v[6:7]
	v_cvt_pk_bf16_f32 v4, v18, v19
	v_cvt_pk_bf16_f32 v5, v8, v9
	v_cvt_pk_bf16_f32 v6, v20, v21
	v_cvt_pk_bf16_f32 v7, v10, v11
	global_store_dwordx4 v[14:15], v[4:7], off
	global_load_dwordx4 v[4:7], v[16:17], off
	v_add_u32_e32 v8, 0x900, v2
	v_ashrrev_i32_e32 v26, 4, v8
	v_mad_u64_u32 v[8:9], s[34:35], v3, s25, v[0:1]
	ds_read_b128 v[8:11], v8
	v_add_u32_e32 v14, s29, v26
	v_ashrrev_i32_e32 v15, 31, v14
	v_lshlrev_b64 v[14:15], 10, v[14:15]
	v_or3_b32 v14, v14, s30, v1
	s_waitcnt lgkmcnt(0)
	v_lshlrev_b32_e32 v18, 16, v8
	v_and_b32_e32 v19, 0xffff0000, v8
	v_lshlrev_b32_e32 v8, 16, v9
	v_and_b32_e32 v9, 0xffff0000, v9
	v_lshlrev_b32_e32 v20, 16, v10
	v_and_b32_e32 v21, 0xffff0000, v10
	v_lshlrev_b32_e32 v10, 16, v11
	v_and_b32_e32 v11, 0xffff0000, v11
	v_lshlrev_b64 v[14:15], 1, v[14:15]
	v_lshl_add_u64 v[16:17], s[12:13], 0, v[14:15]
	v_add_u32_e32 v3, 0xa00, v2
	v_ashrrev_i32_e32 v3, 4, v3
	v_lshl_add_u64 v[14:15], s[2:3], 0, v[14:15]
	s_waitcnt vmcnt(0)
; DI unsigned cvtpk(float lo, float hi) { const f32x2_ v = {lo, hi}; return __builtin_bit_cast(unsigned, __builtin_convertvector(v, bf16x2_)); }
; DI float bflo(unsigned w) { return __uint_as_float(w << 16); }
; DI float bfhi(unsigned w) { return __uint_as_float(w & 0xffff0000u); }
; DI void phase9(const Params& p, const Sched& sched, unsigned char* smem) {
;     ...
; #pragma unroll
;       for (int i = 0; i < 16; ++i) {
;         const int c = tid + 256 * i, row = c >> 4, ch = (c & 15) * 8;
;         const size_t gi = (size_t)(tm * 256 + row) * 1024 + tn * 128 + ch;
;         const u32x4 sv = *(const u32x4*)(Ls + row * EST + ch), xv = *(const u32x4*)(x1b + gi);
;         u32x4 w;
;         w.x = cvtpk(bflo(xv.x) + bflo(sv.x), bfhi(xv.x) + bfhi(sv.x)); w.y = cvtpk(bflo(xv.y) + bflo(sv.y), bfhi(xv.y) + bfhi(sv.y));
;         w.z = cvtpk(bflo(xv.z) + bflo(sv.z), bfhi(xv.z) + bfhi(sv.z)); w.w = cvtpk(bflo(xv.w) + bflo(sv.w), bfhi(xv.w) + bfhi(sv.w));
;         *(u32x4*)(x2b + gi) = w;
;       }
	v_lshlrev_b32_e32 v22, 16, v4
	v_and_b32_e32 v23, 0xffff0000, v4
	v_lshlrev_b32_e32 v4, 16, v5
	v_and_b32_e32 v5, 0xffff0000, v5
	v_lshlrev_b32_e32 v24, 16, v6
	v_and_b32_e32 v25, 0xffff0000, v6
	v_lshlrev_b32_e32 v6, 16, v7
	v_and_b32_e32 v7, 0xffff0000, v7
	v_pk_add_f32 v[18:19], v[18:19], v[22:23]
	v_pk_add_f32 v[8:9], v[8:9], v[4:5]
	v_pk_add_f32 v[20:21], v[20:21], v[24:25]
	v_pk_add_f32 v[10:11], v[10:11], v[6:7]
	v_cvt_pk_bf16_f32 v4, v18, v19
	v_cvt_pk_bf16_f32 v5, v8, v9
	v_cvt_pk_bf16_f32 v6, v20, v21
	v_cvt_pk_bf16_f32 v7, v10, v11
	global_store_dwordx4 v[12:13], v[4:7], off
	global_load_dwordx4 v[4:7], v[16:17], off
	v_mad_u64_u32 v[8:9], s[34:35], v26, s25, v[0:1]
	ds_read_b128 v[8:11], v8
	v_add_u32_e32 v12, s29, v3
	v_ashrrev_i32_e32 v13, 31, v12
	v_lshlrev_b64 v[12:13], 10, v[12:13]
	v_or3_b32 v12, v12, s30, v1
	s_waitcnt lgkmcnt(0)
	v_lshlrev_b32_e32 v18, 16, v8
	v_and_b32_e32 v19, 0xffff0000, v8
	v_lshlrev_b32_e32 v8, 16, v9
	v_and_b32_e32 v9, 0xffff0000, v9
	v_lshlrev_b32_e32 v20, 16, v10
	v_and_b32_e32 v21, 0xffff0000, v10
	v_lshlrev_b32_e32 v10, 16, v11
	v_and_b32_e32 v11, 0xffff0000, v11
	v_lshlrev_b64 v[12:13], 1, v[12:13]
	v_lshl_add_u64 v[16:17], s[12:13], 0, v[12:13]
	v_lshl_add_u64 v[12:13], s[2:3], 0, v[12:13]
	s_waitcnt vmcnt(0)
	v_lshlrev_b32_e32 v22, 16, v4
	v_and_b32_e32 v23, 0xffff0000, v4
	v_lshlrev_b32_e32 v4, 16, v5
	v_and_b32_e32 v5, 0xffff0000, v5
	v_lshlrev_b32_e32 v24, 16, v6
	v_and_b32_e32 v25, 0xffff0000, v6
	v_lshlrev_b32_e32 v6, 16, v7
	v_and_b32_e32 v7, 0xffff0000, v7
	v_pk_add_f32 v[18:19], v[18:19], v[22:23]
	v_pk_add_f32 v[8:9], v[8:9], v[4:5]
	v_pk_add_f32 v[20:21], v[20:21], v[24:25]
	v_pk_add_f32 v[10:11], v[10:11], v[6:7]
	v_cvt_pk_bf16_f32 v4, v18, v19
	v_cvt_pk_bf16_f32 v5, v8, v9
	v_cvt_pk_bf16_f32 v6, v20, v21
	v_cvt_pk_bf16_f32 v7, v10, v11
	global_store_dwordx4 v[14:15], v[4:7], off
	global_load_dwordx4 v[4:7], v[16:17], off
	v_add_u32_e32 v8, 0xb00, v2
	v_ashrrev_i32_e32 v26, 4, v8
	v_mad_u64_u32 v[8:9], s[34:35], v3, s25, v[0:1]
	ds_read_b128 v[8:11], v8
	v_add_u32_e32 v14, s29, v26
	v_ashrrev_i32_e32 v15, 31, v14
	v_lshlrev_b64 v[14:15], 10, v[14:15]
	v_or3_b32 v14, v14, s30, v1
	s_waitcnt lgkmcnt(0)
	v_lshlrev_b32_e32 v18, 16, v8
	v_and_b32_e32 v19, 0xffff0000, v8
	v_lshlrev_b32_e32 v8, 16, v9
	v_and_b32_e32 v9, 0xffff0000, v9
	v_lshlrev_b32_e32 v20, 16, v10
	v_and_b32_e32 v21, 0xffff0000, v10
	v_lshlrev_b32_e32 v10, 16, v11
	v_and_b32_e32 v11, 0xffff0000, v11
	v_lshlrev_b64 v[14:15], 1, v[14:15]
	v_lshl_add_u64 v[16:17], s[12:13], 0, v[14:15]
	v_add_u32_e32 v3, 0xc00, v2
	v_ashrrev_i32_e32 v3, 4, v3
	v_lshl_add_u64 v[14:15], s[2:3], 0, v[14:15]
	s_waitcnt vmcnt(0)
	v_lshlrev_b32_e32 v22, 16, v4
	v_and_b32_e32 v23, 0xffff0000, v4
	v_lshlrev_b32_e32 v4, 16, v5
	v_and_b32_e32 v5, 0xffff0000, v5
	v_lshlrev_b32_e32 v24, 16, v6
	v_and_b32_e32 v25, 0xffff0000, v6
	v_lshlrev_b32_e32 v6, 16, v7
	v_and_b32_e32 v7, 0xffff0000, v7
	v_pk_add_f32 v[18:19], v[18:19], v[22:23]
	v_pk_add_f32 v[8:9], v[8:9], v[4:5]
	v_pk_add_f32 v[20:21], v[20:21], v[24:25]
	v_pk_add_f32 v[10:11], v[10:11], v[6:7]
	v_cvt_pk_bf16_f32 v4, v18, v19
	v_cvt_pk_bf16_f32 v5, v8, v9
	v_cvt_pk_bf16_f32 v6, v20, v21
	v_cvt_pk_bf16_f32 v7, v10, v11
	global_store_dwordx4 v[12:13], v[4:7], off
	global_load_dwordx4 v[4:7], v[16:17], off
	v_mad_u64_u32 v[8:9], s[34:35], v26, s25, v[0:1]
	ds_read_b128 v[8:11], v8
	v_add_u32_e32 v12, s29, v3
	v_ashrrev_i32_e32 v13, 31, v12
	v_lshlrev_b64 v[12:13], 10, v[12:13]
	v_or3_b32 v12, v12, s30, v1
	s_waitcnt lgkmcnt(0)
	v_lshlrev_b32_e32 v18, 16, v8
	v_and_b32_e32 v19, 0xffff0000, v8
	v_lshlrev_b32_e32 v8, 16, v9
	v_and_b32_e32 v9, 0xffff0000, v9
	v_lshlrev_b32_e32 v20, 16, v10
	v_and_b32_e32 v21, 0xffff0000, v10
	v_lshlrev_b32_e32 v10, 16, v11
	v_and_b32_e32 v11, 0xffff0000, v11
	v_lshlrev_b64 v[12:13], 1, v[12:13]
	v_lshl_add_u64 v[16:17], s[12:13], 0, v[12:13]
	v_lshl_add_u64 v[12:13], s[2:3], 0, v[12:13]
	s_waitcnt vmcnt(0)
	v_lshlrev_b32_e32 v22, 16, v4
	v_and_b32_e32 v23, 0xffff0000, v4
	v_lshlrev_b32_e32 v4, 16, v5
	v_and_b32_e32 v5, 0xffff0000, v5
	v_lshlrev_b32_e32 v24, 16, v6
	v_and_b32_e32 v25, 0xffff0000, v6
	v_lshlrev_b32_e32 v6, 16, v7
	v_and_b32_e32 v7, 0xffff0000, v7
	v_pk_add_f32 v[18:19], v[18:19], v[22:23]
	v_pk_add_f32 v[8:9], v[8:9], v[4:5]
	v_pk_add_f32 v[20:21], v[20:21], v[24:25]
	v_pk_add_f32 v[10:11], v[10:11], v[6:7]
	v_cvt_pk_bf16_f32 v4, v18, v19
	v_cvt_pk_bf16_f32 v5, v8, v9
	v_cvt_pk_bf16_f32 v6, v20, v21
	v_cvt_pk_bf16_f32 v7, v10, v11
	global_store_dwordx4 v[14:15], v[4:7], off
	global_load_dwordx4 v[4:7], v[16:17], off
	v_add_u32_e32 v8, 0xd00, v2
	v_ashrrev_i32_e32 v26, 4, v8
	v_mad_u64_u32 v[8:9], s[34:35], v3, s25, v[0:1]
	ds_read_b128 v[8:11], v8
	v_add_u32_e32 v14, s29, v26
	v_ashrrev_i32_e32 v15, 31, v14
	v_lshlrev_b64 v[14:15], 10, v[14:15]
	v_or3_b32 v14, v14, s30, v1
	s_waitcnt lgkmcnt(0)
; DI unsigned cvtpk(float lo, float hi) { const f32x2_ v = {lo, hi}; return __builtin_bit_cast(unsigned, __builtin_convertvector(v, bf16x2_)); }
; DI float bflo(unsigned w) { return __uint_as_float(w << 16); }
; DI float bfhi(unsigned w) { return __uint_as_float(w & 0xffff0000u); }
; template <class F> DI void for_tiles_st(int ntm, int ntn, const Sched& sc, F f) {
;     ...
;     for (int sp = sc.xd; sp < nsuper; sp += sc.nx) {
;       const int sm = sp / nsn, sn = sp - sm * nsn;
;       for (int qq = sc.rank; qq < 64; qq += sc.nloc) f(sm * 8 + (qq >> 3), sn * 8 + (qq & 7));
; DI void phase9(const Params& p, const Sched& sched, unsigned char* smem) {
;     ...
; #pragma unroll
;       for (int i = 0; i < 16; ++i) {
;         const int c = tid + 256 * i, row = c >> 4, ch = (c & 15) * 8;
;         const size_t gi = (size_t)(tm * 256 + row) * 1024 + tn * 128 + ch;
;         const u32x4 sv = *(const u32x4*)(Ls + row * EST + ch), xv = *(const u32x4*)(x1b + gi);
;         u32x4 w;
;         w.x = cvtpk(bflo(xv.x) + bflo(sv.x), bfhi(xv.x) + bfhi(sv.x)); w.y = cvtpk(bflo(xv.y) + bflo(sv.y), bfhi(xv.y) + bfhi(sv.y));
;         w.z = cvtpk(bflo(xv.z) + bflo(sv.z), bfhi(xv.z) + bfhi(sv.z)); w.w = cvtpk(bflo(xv.w) + bflo(sv.w), bfhi(xv.w) + bfhi(sv.w));
;         *(u32x4*)(x2b + gi) = w;
;       }
	v_lshlrev_b32_e32 v18, 16, v8
	v_and_b32_e32 v19, 0xffff0000, v8
	v_lshlrev_b32_e32 v8, 16, v9
	v_and_b32_e32 v9, 0xffff0000, v9
	v_lshlrev_b32_e32 v20, 16, v10
	v_and_b32_e32 v21, 0xffff0000, v10
	v_lshlrev_b32_e32 v10, 16, v11
	v_and_b32_e32 v11, 0xffff0000, v11
	v_lshlrev_b64 v[14:15], 1, v[14:15]
	v_lshl_add_u64 v[16:17], s[12:13], 0, v[14:15]
	v_add_u32_e32 v3, 0xe00, v2
	v_ashrrev_i32_e32 v3, 4, v3
	v_lshl_add_u64 v[14:15], s[2:3], 0, v[14:15]
	v_add_u32_e32 v2, 0xf00, v2
	s_waitcnt vmcnt(0)
	v_lshlrev_b32_e32 v22, 16, v4
	v_and_b32_e32 v23, 0xffff0000, v4
	v_lshlrev_b32_e32 v4, 16, v5
	v_and_b32_e32 v5, 0xffff0000, v5
	v_lshlrev_b32_e32 v24, 16, v6
	v_and_b32_e32 v25, 0xffff0000, v6
	v_lshlrev_b32_e32 v6, 16, v7
	v_and_b32_e32 v7, 0xffff0000, v7
	v_pk_add_f32 v[18:19], v[18:19], v[22:23]
	v_pk_add_f32 v[8:9], v[8:9], v[4:5]
	v_pk_add_f32 v[20:21], v[20:21], v[24:25]
	v_pk_add_f32 v[10:11], v[10:11], v[6:7]
	v_cvt_pk_bf16_f32 v4, v18, v19
	v_cvt_pk_bf16_f32 v5, v8, v9
	v_cvt_pk_bf16_f32 v6, v20, v21
	v_cvt_pk_bf16_f32 v7, v10, v11
	global_store_dwordx4 v[12:13], v[4:7], off
	global_load_dwordx4 v[4:7], v[16:17], off
	v_mad_u64_u32 v[8:9], s[34:35], v26, s25, v[0:1]
	ds_read_b128 v[8:11], v8
	v_add_u32_e32 v12, s29, v3
	v_ashrrev_i32_e32 v13, 31, v12
	v_lshlrev_b64 v[12:13], 10, v[12:13]
	v_or3_b32 v12, v12, s30, v1
	s_waitcnt lgkmcnt(0)
	v_lshlrev_b32_e32 v18, 16, v8
	v_and_b32_e32 v19, 0xffff0000, v8
	v_lshlrev_b32_e32 v8, 16, v9
	v_and_b32_e32 v9, 0xffff0000, v9
	v_lshlrev_b32_e32 v20, 16, v10
	v_and_b32_e32 v21, 0xffff0000, v10
	v_lshlrev_b32_e32 v10, 16, v11
	v_and_b32_e32 v11, 0xffff0000, v11
	v_lshlrev_b64 v[12:13], 1, v[12:13]
	v_lshl_add_u64 v[16:17], s[12:13], 0, v[12:13]
	v_lshl_add_u64 v[12:13], s[2:3], 0, v[12:13]
	s_waitcnt vmcnt(0)
	v_lshlrev_b32_e32 v22, 16, v4
	v_and_b32_e32 v23, 0xffff0000, v4
	v_lshlrev_b32_e32 v4, 16, v5
	v_and_b32_e32 v5, 0xffff0000, v5
	v_lshlrev_b32_e32 v24, 16, v6
	v_and_b32_e32 v25, 0xffff0000, v6
	v_lshlrev_b32_e32 v6, 16, v7
	v_and_b32_e32 v7, 0xffff0000, v7
	v_pk_add_f32 v[18:19], v[18:19], v[22:23]
	v_pk_add_f32 v[8:9], v[8:9], v[4:5]
	v_pk_add_f32 v[20:21], v[20:21], v[24:25]
	v_pk_add_f32 v[10:11], v[10:11], v[6:7]
	v_cvt_pk_bf16_f32 v4, v18, v19
	v_cvt_pk_bf16_f32 v5, v8, v9
	v_cvt_pk_bf16_f32 v6, v20, v21
	v_cvt_pk_bf16_f32 v7, v10, v11
	global_store_dwordx4 v[14:15], v[4:7], off
	global_load_dwordx4 v[4:7], v[16:17], off
	v_mad_u64_u32 v[8:9], s[34:35], v3, s25, v[0:1]
	v_ashrrev_i32_e32 v24, 4, v2
	ds_read_b128 v[8:11], v8
	v_add_u32_e32 v2, s29, v24
	v_ashrrev_i32_e32 v3, 31, v2
	v_lshlrev_b64 v[2:3], 10, v[2:3]
	v_or3_b32 v2, v2, s30, v1
	v_lshlrev_b64 v[14:15], 1, v[2:3]
	s_waitcnt lgkmcnt(0)
	v_lshlrev_b32_e32 v2, 16, v8
	v_and_b32_e32 v3, 0xffff0000, v8
	v_lshlrev_b32_e32 v8, 16, v9
	v_and_b32_e32 v9, 0xffff0000, v9
	v_lshlrev_b32_e32 v18, 16, v10
	v_and_b32_e32 v19, 0xffff0000, v10
	v_lshlrev_b32_e32 v10, 16, v11
	v_and_b32_e32 v11, 0xffff0000, v11
	v_lshl_add_u64 v[16:17], s[12:13], 0, v[14:15]
	v_mad_u64_u32 v[0:1], s[30:31], v24, s25, v[0:1]
	s_waitcnt vmcnt(0)
	v_lshlrev_b32_e32 v20, 16, v4
	v_and_b32_e32 v21, 0xffff0000, v4
	v_lshlrev_b32_e32 v4, 16, v5
	v_and_b32_e32 v5, 0xffff0000, v5
	v_lshlrev_b32_e32 v22, 16, v6
	v_and_b32_e32 v23, 0xffff0000, v6
	v_lshlrev_b32_e32 v6, 16, v7
	v_and_b32_e32 v7, 0xffff0000, v7
	v_pk_add_f32 v[2:3], v[2:3], v[20:21]
	v_pk_add_f32 v[4:5], v[8:9], v[4:5]
	v_pk_add_f32 v[8:9], v[18:19], v[22:23]
	v_pk_add_f32 v[6:7], v[10:11], v[6:7]
	v_cvt_pk_bf16_f32 v2, v2, v3
	v_cvt_pk_bf16_f32 v3, v4, v5
	v_cvt_pk_bf16_f32 v4, v8, v9
	v_cvt_pk_bf16_f32 v5, v6, v7
	global_store_dwordx4 v[12:13], v[2:5], off
	global_load_dwordx4 v[2:5], v[16:17], off
	ds_read_b128 v[6:9], v0
	v_lshl_add_u64 v[10:11], s[2:3], 0, v[14:15]
	s_waitcnt lgkmcnt(0)
	v_lshlrev_b32_e32 v0, 16, v6
	v_and_b32_e32 v1, 0xffff0000, v6
	v_lshlrev_b32_e32 v6, 16, v7
	v_and_b32_e32 v7, 0xffff0000, v7
	v_lshlrev_b32_e32 v12, 16, v8
	v_and_b32_e32 v13, 0xffff0000, v8
	v_lshlrev_b32_e32 v8, 16, v9
	v_and_b32_e32 v9, 0xffff0000, v9
	s_waitcnt vmcnt(0)
	v_lshlrev_b32_e32 v14, 16, v2
	v_and_b32_e32 v15, 0xffff0000, v2
	v_lshlrev_b32_e32 v2, 16, v3
	v_and_b32_e32 v3, 0xffff0000, v3
	v_lshlrev_b32_e32 v16, 16, v4
	v_and_b32_e32 v17, 0xffff0000, v4
	v_lshlrev_b32_e32 v4, 16, v5
	v_and_b32_e32 v5, 0xffff0000, v5
	v_pk_add_f32 v[0:1], v[0:1], v[14:15]
	v_pk_add_f32 v[2:3], v[6:7], v[2:3]
	v_pk_add_f32 v[6:7], v[12:13], v[16:17]
	v_pk_add_f32 v[4:5], v[8:9], v[4:5]
	v_cvt_pk_bf16_f32 v0, v0, v1
	v_cvt_pk_bf16_f32 v1, v2, v3
	v_cvt_pk_bf16_f32 v2, v6, v7
	v_cvt_pk_bf16_f32 v3, v4, v5
	global_store_dwordx4 v[10:11], v[0:3], off
	v_mov_b32_e32 v243, 0x12000
	v_readfirstlane_b32 s98, v218
	s_cmp_lg_u32 s98, 0
	s_cbranch_scc1 .Lp9_dyn_skip_b
	s_waitcnt vmcnt(16)
	s_mov_b64 s[100:101], exec
	s_mov_b64 exec, 1
	ds_write_b32 v243, v240
	s_waitcnt lgkmcnt(0)
	s_mov_b64 exec, s[100:101]

; template <class F> DI void for_tiles_st(int ntm, int ntn, const Sched& sc, F f) {
;     ...
;     for (int sp = sc.xd; sp < nsuper; sp += sc.nx) {
;       const int sm = sp / nsn, sn = sp - sm * nsn;
;       for (int qq = sc.rank; qq < 64; qq += sc.nloc) f(sm * 8 + (qq >> 3), sn * 8 + (qq & 7));
.Lp9_dyn_decode_n:
	s_and_b32 s28, s98, 63
	s_mov_b32 s27, s28
	s_lshr_b32 s99, s98, 6
	s_mul_i32 s99, s99, s79
	s_add_i32 s99, s99, s74
	s_cmp_gt_i32 s99, 31
	s_cbranch_scc1 .LBB0_1097
	s_lshl_b32 s26, s99, 3
	s_mov_b32 s18, s26
	s_branch .LBB0_1094
